# fix-up phase: the 32 surplus (tile, half) items no longer double four workgroups' work; each is split two rows per wave across the waves of workgroups 0-31
# speedup vs baseline: 1.0214x; 1.0174x over previous
; __device__ __forceinline__ int tid_() { int t = threadIdx.x; asm volatile("" : "+v"(t)); return t; }
; __device__ __forceinline__ int bid_() { int t = blockIdx.x; asm volatile("" : "+s"(t)); return t; }
; __device__ __forceinline__ int gdim_() { int t = gridDim.x; asm volatile("" : "+s"(t)); return t; }
; __device__ __forceinline__ void fixup_phase(KP p, int l) {
;     bf16_t* P = (bf16_t*)(p->ws + WS_BIG);
;     const bf16_t* HLOC = (const bf16_t*)(p->ws + WS_R2); const bf16_t* PCUM = (const bf16_t*)(p->ws + WS_R2 + R2_PCUM);
;     const float* SUMM = (const float*)(p->ws + WS_SUMM);
;     const int gt = bid_() * 512 + tid_(), NT = gdim_() * 512;
;     for (int it = gt; it < (M / 16) * 128; it += NT) {
;         const int tile = it >> 7, c0 = (it & 127) * 8, m0 = tile * 16;
.LBB0_409:
	s_or_b64 exec, exec, s[4:5]
	s_mov_b64 s[6:7], s[94:95]
	s_mov_b32 s4, s2
	v_mov_b32_e32 v0, v209
	s_waitcnt lgkmcnt(0)
	s_barrier
	s_mov_b64 s[8:9], exec
	s_lshl_b32 s16, s3, 9
	s_lshl_b32 s18, s56, 3
	s_lshl_b32 s19, s3, 12
	s_load_dwordx2 s[34:35], s[6:7], 0xe8
	s_load_dwordx2 s[72:73], s[6:7], 0xe0
	v_readfirstlane_b32 s5, v0
	v_and_b32_e32 v2, 63, v0
	s_nop 2
	s_lshr_b32 s5, s5, 6
	s_lshl_b32 s5, s5, 6
	s_lshl_b32 s57, s4, 9
	s_add_i32 s57, s57, s5
	s_mov_b32 s87, 0
	s_waitcnt lgkmcnt(0)

; __device__ __forceinline__ u32x4 pack8(const float (&f)[8]) { u32x4 o; o.x = cvt_pk_bf16(f[0], f[1]); o.y = cvt_pk_bf16(f[2], f[3]); o.z = cvt_pk_bf16(f[4], f[5]); o.w = cvt_pk_bf16(f[6], f[7]); return o; }
; __device__ __forceinline__ float gelu_tanh(float x) { return x * sigmoidf_(1.5957691216057308f * (x + 0.044715f * x * x * x)); }
; __device__ __forceinline__ void fixup_phase(KP p, int l) {
;     ...
; #pragma unroll 4
;         for (int i = 0; i < 16; ++i) {
;             const size_t m = (size_t)(m0 + i);
;             float hl[8], pc[8], gr[8], o[8], h[8];
;             unpack8(__builtin_nontemporal_load((const u32x4*)(HLOC + m * D + c0)), hl); unpack8(__builtin_nontemporal_load((const u32x4*)(PCUM + m * D + c0)), pc);
;             bf16_t* gp = P + m * DP + C_GR + c0; unpack8(*(const u32x4*)gp, gr);
; #pragma unroll
;             for (int e = 0; e < 8; ++e) { h[e] = hl[e] + pc[e] * carry[e]; o[e] = gelu_tanh(gr[e]) * h[e]; }
;             *(u32x4*)gp = pack8(o);
.Lfx_nocarry:
	s_lshl_b32 s44, s48, 12
	s_add_u32 s12, s34, 0x14a48000
	s_addc_u32 s13, s35, 0
	s_add_u32 s12, s12, s44
	s_addc_u32 s13, s13, 0
	s_add_u32 s14, s12, 0x2080000
	s_addc_u32 s15, s13, 0
	s_mul_i32 s44, s48, 0x2800
	s_add_u32 s96, s34, 0x66c9800
	s_addc_u32 s97, s35, 0
	s_add_u32 s96, s96, s44
	s_addc_u32 s97, s97, 0
	s_mov_b32 s24, s96
	s_mov_b32 s25, s97
	s_cmp_eq_u32 s87, 0
	s_cbranch_scc1 .Lfx_rows16
	s_lshr_b32 s44, s5, 5
	s_lshl_b32 s23, s44, 12
	s_add_u32 s12, s12, s23
	s_addc_u32 s13, s13, 0
	s_add_u32 s14, s14, s23
	s_addc_u32 s15, s15, 0
	s_mul_i32 s23, s44, 0x2800
	s_add_u32 s96, s96, s23
	s_addc_u32 s97, s97, 0
	s_mov_b32 s24, s96
	s_mov_b32 s25, s97
	global_load_dwordx4 v[32:35], v31, s[12:13]
	global_load_dwordx4 v[36:39], v31, s[12:13] offset:16
	global_load_dwordx4 v[40:43], v26, s[96:97] nt
	s_add_u32 s12, s12, 0x1000
	s_addc_u32 s13, s13, 0
	s_add_u32 s96, s96, 0x2800
	s_addc_u32 s97, s97, 0
	global_load_dwordx4 v[44:47], v31, s[12:13]
	global_load_dwordx4 v[48:51], v31, s[12:13] offset:16
	global_load_dwordx4 v[52:55], v26, s[96:97] nt
	s_add_u32 s12, s12, 0x1000
	s_addc_u32 s13, s13, 0
	s_add_u32 s96, s96, 0x2800
	s_addc_u32 s97, s97, 0
	s_waitcnt vmcnt(3)
	v_lshlrev_b32_e32 v80, 16, v32
	v_and_b32_e32 v96, 0xffff0000, v32
	v_lshlrev_b32_e32 v81, 16, v33
	v_and_b32_e32 v97, 0xffff0000, v33
	v_lshlrev_b32_e32 v82, 16, v34
	v_and_b32_e32 v98, 0xffff0000, v34
	v_lshlrev_b32_e32 v83, 16, v35
	v_and_b32_e32 v99, 0xffff0000, v35
	v_lshlrev_b32_e32 v84, 16, v36
	v_and_b32_e32 v100, 0xffff0000, v36
	v_lshlrev_b32_e32 v85, 16, v37
	v_and_b32_e32 v101, 0xffff0000, v37
	v_lshlrev_b32_e32 v86, 16, v38
	v_and_b32_e32 v102, 0xffff0000, v38
	v_lshlrev_b32_e32 v87, 16, v39
	v_and_b32_e32 v103, 0xffff0000, v39
	v_lshlrev_b32_e32 v88, 16, v40
	v_and_b32_e32 v89, 0xffff0000, v40
	v_lshlrev_b32_e32 v90, 16, v41
	v_and_b32_e32 v91, 0xffff0000, v41
	v_lshlrev_b32_e32 v92, 16, v42
	v_and_b32_e32 v93, 0xffff0000, v42
	v_lshlrev_b32_e32 v94, 16, v43
	v_and_b32_e32 v95, 0xffff0000, v43
	v_fmac_f32_e32 v80, v96, v18
	v_fmac_f32_e32 v81, v97, v19
	v_fmac_f32_e32 v82, v98, v20
	v_fmac_f32_e32 v83, v99, v21
	v_fmac_f32_e32 v84, v100, v22
	v_fmac_f32_e32 v85, v101, v23
	v_fmac_f32_e32 v86, v102, v24
	v_fmac_f32_e32 v87, v103, v25
	v_mul_f32_e32 v104, 0x3d372713, v88
	v_mul_f32_e32 v105, 0x3d372713, v89
	v_mul_f32_e32 v106, 0x3d372713, v90
	v_mul_f32_e32 v107, 0x3d372713, v91
	v_mul_f32_e32 v108, 0x3d372713, v92
	v_mul_f32_e32 v109, 0x3d372713, v93
	v_mul_f32_e32 v110, 0x3d372713, v94
	v_mul_f32_e32 v111, 0x3d372713, v95
	v_mul_f32_e32 v104, v104, v88
	v_mul_f32_e32 v105, v105, v89
	v_mul_f32_e32 v106, v106, v90
	v_mul_f32_e32 v107, v107, v91
	v_mul_f32_e32 v108, v108, v92
	v_mul_f32_e32 v109, v109, v93
	v_mul_f32_e32 v110, v110, v94
	v_mul_f32_e32 v111, v111, v95
	v_fma_f32 v104, v104, v88, v88
	v_fma_f32 v105, v105, v89, v89
	v_fma_f32 v106, v106, v90, v90
	v_fma_f32 v107, v107, v91, v91
	v_fma_f32 v108, v108, v92, v92
	v_fma_f32 v109, v109, v93, v93
	v_fma_f32 v110, v110, v94, v94
	v_fma_f32 v111, v111, v95, v95
	v_mul_f32_e32 v104, 0x3fcc422a, v104
	v_mul_f32_e32 v105, 0x3fcc422a, v105
	v_mul_f32_e32 v106, 0x3fcc422a, v106
	v_mul_f32_e32 v107, 0x3fcc422a, v107
	v_mul_f32_e32 v108, 0x3fcc422a, v108
	v_mul_f32_e32 v109, 0x3fcc422a, v109
	v_mul_f32_e32 v110, 0x3fcc422a, v110
	v_mul_f32_e32 v111, 0x3fcc422a, v111
	v_mul_f32_e32 v104, 0xbfb8aa3b, v104
	v_mul_f32_e32 v105, 0xbfb8aa3b, v105
	v_mul_f32_e32 v106, 0xbfb8aa3b, v106
	v_mul_f32_e32 v107, 0xbfb8aa3b, v107
	v_mul_f32_e32 v108, 0xbfb8aa3b, v108
	v_mul_f32_e32 v109, 0xbfb8aa3b, v109
	v_mul_f32_e32 v110, 0xbfb8aa3b, v110
	v_mul_f32_e32 v111, 0xbfb8aa3b, v111
	v_exp_f32_e32 v104, v104
	v_exp_f32_e32 v105, v105
	v_exp_f32_e32 v106, v106
	v_exp_f32_e32 v107, v107
	v_exp_f32_e32 v108, v108
	v_exp_f32_e32 v109, v109
	v_exp_f32_e32 v110, v110
	v_exp_f32_e32 v111, v111
	v_add_f32_e32 v104, 1.0, v104
	v_add_f32_e32 v105, 1.0, v105
	v_add_f32_e32 v106, 1.0, v106
	v_add_f32_e32 v107, 1.0, v107
	v_add_f32_e32 v108, 1.0, v108
	v_add_f32_e32 v109, 1.0, v109
	v_add_f32_e32 v110, 1.0, v110
	v_add_f32_e32 v111, 1.0, v111
	v_rcp_f32_e32 v104, v104
	v_rcp_f32_e32 v105, v105
	v_rcp_f32_e32 v106, v106
	v_rcp_f32_e32 v107, v107
	v_rcp_f32_e32 v108, v108
	v_rcp_f32_e32 v109, v109
	v_rcp_f32_e32 v110, v110
	v_rcp_f32_e32 v111, v111
	v_mul_f32_e32 v104, v104, v88
	v_mul_f32_e32 v105, v105, v89
	v_mul_f32_e32 v106, v106, v90
	v_mul_f32_e32 v107, v107, v91
	v_mul_f32_e32 v108, v108, v92
	v_mul_f32_e32 v109, v109, v93
	v_mul_f32_e32 v110, v110, v94
	v_mul_f32_e32 v111, v111, v95
	v_mul_f32_e32 v104, v80, v104
	v_mul_f32_e32 v105, v81, v105
	v_mul_f32_e32 v106, v82, v106
	v_mul_f32_e32 v107, v83, v107
	v_mul_f32_e32 v108, v84, v108
	v_mul_f32_e32 v109, v85, v109
	v_mul_f32_e32 v110, v86, v110
	v_mul_f32_e32 v111, v87, v111
	v_cvt_pk_bf16_f32 v112, v104, v105
	v_cvt_pk_bf16_f32 v113, v106, v107
	v_cvt_pk_bf16_f32 v114, v108, v109
	v_cvt_pk_bf16_f32 v115, v110, v111
	global_store_dwordx4 v27, v[112:115], s[24:25]
	s_add_u32 s24, s24, 0x2800
	s_addc_u32 s25, s25, 0
	s_waitcnt vmcnt(1)
; __device__ __forceinline__ u32x4 pack8(const float (&f)[8]) { u32x4 o; o.x = cvt_pk_bf16(f[0], f[1]); o.y = cvt_pk_bf16(f[2], f[3]); o.z = cvt_pk_bf16(f[4], f[5]); o.w = cvt_pk_bf16(f[6], f[7]); return o; }
; __device__ __forceinline__ float gelu_tanh(float x) { return x * sigmoidf_(1.5957691216057308f * (x + 0.044715f * x * x * x)); }
; __device__ __forceinline__ void fixup_phase(KP p, int l) {
;     ...
;         for (int i = 0; i < 16; ++i) {
;             const size_t m = (size_t)(m0 + i);
;             float hl[8], pc[8], gr[8], o[8], h[8];
;             unpack8(__builtin_nontemporal_load((const u32x4*)(HLOC + m * D + c0)), hl); unpack8(__builtin_nontemporal_load((const u32x4*)(PCUM + m * D + c0)), pc);
;             bf16_t* gp = P + m * DP + C_GR + c0; unpack8(*(const u32x4*)gp, gr);
; #pragma unroll
;             for (int e = 0; e < 8; ++e) { h[e] = hl[e] + pc[e] * carry[e]; o[e] = gelu_tanh(gr[e]) * h[e]; }
;             *(u32x4*)gp = pack8(o);
;             if (tile < 1032 && t0 + i == TP - 1) store8f(p->out + O_PRG + (size_t)(l * NB + b) * D + c0, h);
	v_lshlrev_b32_e32 v80, 16, v44
	v_and_b32_e32 v96, 0xffff0000, v44
	v_lshlrev_b32_e32 v81, 16, v45
	v_and_b32_e32 v97, 0xffff0000, v45
	v_lshlrev_b32_e32 v82, 16, v46
	v_and_b32_e32 v98, 0xffff0000, v46
	v_lshlrev_b32_e32 v83, 16, v47
	v_and_b32_e32 v99, 0xffff0000, v47
	v_lshlrev_b32_e32 v84, 16, v48
	v_and_b32_e32 v100, 0xffff0000, v48
	v_lshlrev_b32_e32 v85, 16, v49
	v_and_b32_e32 v101, 0xffff0000, v49
	v_lshlrev_b32_e32 v86, 16, v50
	v_and_b32_e32 v102, 0xffff0000, v50
	v_lshlrev_b32_e32 v87, 16, v51
	v_and_b32_e32 v103, 0xffff0000, v51
	v_lshlrev_b32_e32 v88, 16, v52
	v_and_b32_e32 v89, 0xffff0000, v52
	v_lshlrev_b32_e32 v90, 16, v53
	v_and_b32_e32 v91, 0xffff0000, v53
	v_lshlrev_b32_e32 v92, 16, v54
	v_and_b32_e32 v93, 0xffff0000, v54
	v_lshlrev_b32_e32 v94, 16, v55
	v_and_b32_e32 v95, 0xffff0000, v55
	v_fmac_f32_e32 v80, v96, v18
	v_fmac_f32_e32 v81, v97, v19
	v_fmac_f32_e32 v82, v98, v20
	v_fmac_f32_e32 v83, v99, v21
	v_fmac_f32_e32 v84, v100, v22
	v_fmac_f32_e32 v85, v101, v23
	v_fmac_f32_e32 v86, v102, v24
	v_fmac_f32_e32 v87, v103, v25
	v_mul_f32_e32 v104, 0x3d372713, v88
	v_mul_f32_e32 v105, 0x3d372713, v89
	v_mul_f32_e32 v106, 0x3d372713, v90
	v_mul_f32_e32 v107, 0x3d372713, v91
	v_mul_f32_e32 v108, 0x3d372713, v92
	v_mul_f32_e32 v109, 0x3d372713, v93
	v_mul_f32_e32 v110, 0x3d372713, v94
	v_mul_f32_e32 v111, 0x3d372713, v95
	v_mul_f32_e32 v104, v104, v88
	v_mul_f32_e32 v105, v105, v89
	v_mul_f32_e32 v106, v106, v90
	v_mul_f32_e32 v107, v107, v91
	v_mul_f32_e32 v108, v108, v92
	v_mul_f32_e32 v109, v109, v93
	v_mul_f32_e32 v110, v110, v94
	v_mul_f32_e32 v111, v111, v95
	v_fma_f32 v104, v104, v88, v88
	v_fma_f32 v105, v105, v89, v89
	v_fma_f32 v106, v106, v90, v90
	v_fma_f32 v107, v107, v91, v91
	v_fma_f32 v108, v108, v92, v92
	v_fma_f32 v109, v109, v93, v93
	v_fma_f32 v110, v110, v94, v94
	v_fma_f32 v111, v111, v95, v95
	v_mul_f32_e32 v104, 0x3fcc422a, v104
	v_mul_f32_e32 v105, 0x3fcc422a, v105
	v_mul_f32_e32 v106, 0x3fcc422a, v106
	v_mul_f32_e32 v107, 0x3fcc422a, v107
	v_mul_f32_e32 v108, 0x3fcc422a, v108
	v_mul_f32_e32 v109, 0x3fcc422a, v109
	v_mul_f32_e32 v110, 0x3fcc422a, v110
	v_mul_f32_e32 v111, 0x3fcc422a, v111
	v_mul_f32_e32 v104, 0xbfb8aa3b, v104
	v_mul_f32_e32 v105, 0xbfb8aa3b, v105
	v_mul_f32_e32 v106, 0xbfb8aa3b, v106
	v_mul_f32_e32 v107, 0xbfb8aa3b, v107
	v_mul_f32_e32 v108, 0xbfb8aa3b, v108
	v_mul_f32_e32 v109, 0xbfb8aa3b, v109
	v_mul_f32_e32 v110, 0xbfb8aa3b, v110
	v_mul_f32_e32 v111, 0xbfb8aa3b, v111
	v_exp_f32_e32 v104, v104
	v_exp_f32_e32 v105, v105
	v_exp_f32_e32 v106, v106
	v_exp_f32_e32 v107, v107
	v_exp_f32_e32 v108, v108
	v_exp_f32_e32 v109, v109
	v_exp_f32_e32 v110, v110
	v_exp_f32_e32 v111, v111
	v_add_f32_e32 v104, 1.0, v104
	v_add_f32_e32 v105, 1.0, v105
	v_add_f32_e32 v106, 1.0, v106
	v_add_f32_e32 v107, 1.0, v107
	v_add_f32_e32 v108, 1.0, v108
	v_add_f32_e32 v109, 1.0, v109
	v_add_f32_e32 v110, 1.0, v110
	v_add_f32_e32 v111, 1.0, v111
	v_rcp_f32_e32 v104, v104
	v_rcp_f32_e32 v105, v105
	v_rcp_f32_e32 v106, v106
	v_rcp_f32_e32 v107, v107
	v_rcp_f32_e32 v108, v108
	v_rcp_f32_e32 v109, v109
	v_rcp_f32_e32 v110, v110
	v_rcp_f32_e32 v111, v111
	v_mul_f32_e32 v104, v104, v88
	v_mul_f32_e32 v105, v105, v89
	v_mul_f32_e32 v106, v106, v90
	v_mul_f32_e32 v107, v107, v91
	v_mul_f32_e32 v108, v108, v92
	v_mul_f32_e32 v109, v109, v93
	v_mul_f32_e32 v110, v110, v94
	v_mul_f32_e32 v111, v111, v95
	v_mul_f32_e32 v104, v80, v104
	v_mul_f32_e32 v105, v81, v105
	v_mul_f32_e32 v106, v82, v106
	v_mul_f32_e32 v107, v83, v107
	v_mul_f32_e32 v108, v84, v108
	v_mul_f32_e32 v109, v85, v109
	v_mul_f32_e32 v110, v86, v110
	v_mul_f32_e32 v111, v87, v111
	v_cvt_pk_bf16_f32 v112, v104, v105
	v_cvt_pk_bf16_f32 v113, v106, v107
	v_cvt_pk_bf16_f32 v114, v108, v109
	v_cvt_pk_bf16_f32 v115, v110, v111
	global_store_dwordx4 v27, v[112:115], s[24:25]
	s_cmp_eq_u32 s43, 0
	s_cbranch_scc1 .Lfx_done
	s_cmp_eq_u32 s5, 0x1c0
	s_cbranch_scc0 .Lfx_done
	s_lshl_b32 s44, s18, 12
	s_lshl_b32 s23, s10, 12
	s_add_i32 s44, s44, s23
	s_add_u32 s98, s72, 0x4120000
	s_addc_u32 s99, s73, 0
	s_add_u32 s98, s98, s44
	s_addc_u32 s99, s99, 0
	global_store_dwordx4 v31, v[80:83], s[98:99]
	global_store_dwordx4 v31, v[84:87], s[98:99] offset:16
	s_branch .Lfx_done
.Lfx_rows16:
	global_load_dwordx4 v[32:35], v31, s[12:13]
	global_load_dwordx4 v[36:39], v31, s[12:13] offset:16
	global_load_dwordx4 v[40:43], v26, s[96:97] nt
	s_add_u32 s12, s12, 0x1000
	s_addc_u32 s13, s13, 0
	s_add_u32 s96, s96, 0x2800
	s_addc_u32 s97, s97, 0
	global_load_dwordx4 v[44:47], v31, s[12:13]
	global_load_dwordx4 v[48:51], v31, s[12:13] offset:16
	global_load_dwordx4 v[52:55], v26, s[96:97] nt
	s_add_u32 s12, s12, 0x1000
	s_addc_u32 s13, s13, 0
	s_add_u32 s96, s96, 0x2800
	s_addc_u32 s97, s97, 0
	global_load_dwordx4 v[56:59], v31, s[12:13]
	global_load_dwordx4 v[60:63], v31, s[12:13] offset:16
	global_load_dwordx4 v[64:67], v26, s[96:97] nt
	s_add_u32 s12, s12, 0x1000
	s_addc_u32 s13, s13, 0
	s_add_u32 s96, s96, 0x2800
	s_addc_u32 s97, s97, 0
	global_load_dwordx4 v[68:71], v31, s[12:13]
	global_load_dwordx4 v[72:75], v31, s[12:13] offset:16
	global_load_dwordx4 v[76:79], v26, s[96:97] nt
	s_add_u32 s12, s12, 0x1000
	s_addc_u32 s13, s13, 0
	s_add_u32 s96, s96, 0x2800
	s_addc_u32 s97, s97, 0
	s_waitcnt vmcnt(9)
; __device__ __forceinline__ u32x4 pack8(const float (&f)[8]) { u32x4 o; o.x = cvt_pk_bf16(f[0], f[1]); o.y = cvt_pk_bf16(f[2], f[3]); o.z = cvt_pk_bf16(f[4], f[5]); o.w = cvt_pk_bf16(f[6], f[7]); return o; }
; __device__ __forceinline__ float gelu_tanh(float x) { return x * sigmoidf_(1.5957691216057308f * (x + 0.044715f * x * x * x)); }
; __device__ __forceinline__ void fixup_phase(KP p, int l) {
;     ...
;         for (int i = 0; i < 16; ++i) {
;             const size_t m = (size_t)(m0 + i);
;             float hl[8], pc[8], gr[8], o[8], h[8];
;             unpack8(__builtin_nontemporal_load((const u32x4*)(HLOC + m * D + c0)), hl); unpack8(__builtin_nontemporal_load((const u32x4*)(PCUM + m * D + c0)), pc);
;             bf16_t* gp = P + m * DP + C_GR + c0; unpack8(*(const u32x4*)gp, gr);
; #pragma unroll
;             for (int e = 0; e < 8; ++e) { h[e] = hl[e] + pc[e] * carry[e]; o[e] = gelu_tanh(gr[e]) * h[e]; }
;             *(u32x4*)gp = pack8(o);
	v_lshlrev_b32_e32 v80, 16, v32
	v_and_b32_e32 v96, 0xffff0000, v32
	v_lshlrev_b32_e32 v81, 16, v33
	v_and_b32_e32 v97, 0xffff0000, v33
	v_lshlrev_b32_e32 v82, 16, v34
	v_and_b32_e32 v98, 0xffff0000, v34
	v_lshlrev_b32_e32 v83, 16, v35
	v_and_b32_e32 v99, 0xffff0000, v35
	v_lshlrev_b32_e32 v84, 16, v36
	v_and_b32_e32 v100, 0xffff0000, v36
	v_lshlrev_b32_e32 v85, 16, v37
	v_and_b32_e32 v101, 0xffff0000, v37
	v_lshlrev_b32_e32 v86, 16, v38
	v_and_b32_e32 v102, 0xffff0000, v38
	v_lshlrev_b32_e32 v87, 16, v39
	v_and_b32_e32 v103, 0xffff0000, v39
	v_lshlrev_b32_e32 v88, 16, v40
	v_and_b32_e32 v89, 0xffff0000, v40
	v_lshlrev_b32_e32 v90, 16, v41
	v_and_b32_e32 v91, 0xffff0000, v41
	v_lshlrev_b32_e32 v92, 16, v42
	v_and_b32_e32 v93, 0xffff0000, v42
	v_lshlrev_b32_e32 v94, 16, v43
	v_and_b32_e32 v95, 0xffff0000, v43
	v_fmac_f32_e32 v80, v96, v18
	v_fmac_f32_e32 v81, v97, v19
	v_fmac_f32_e32 v82, v98, v20
	v_fmac_f32_e32 v83, v99, v21
	v_fmac_f32_e32 v84, v100, v22
	v_fmac_f32_e32 v85, v101, v23
	v_fmac_f32_e32 v86, v102, v24
	v_fmac_f32_e32 v87, v103, v25
	v_mul_f32_e32 v104, 0x3d372713, v88
	v_mul_f32_e32 v105, 0x3d372713, v89
	v_mul_f32_e32 v106, 0x3d372713, v90
	v_mul_f32_e32 v107, 0x3d372713, v91
	v_mul_f32_e32 v108, 0x3d372713, v92
	v_mul_f32_e32 v109, 0x3d372713, v93
	v_mul_f32_e32 v110, 0x3d372713, v94
	v_mul_f32_e32 v111, 0x3d372713, v95
	v_mul_f32_e32 v104, v104, v88
	v_mul_f32_e32 v105, v105, v89
	v_mul_f32_e32 v106, v106, v90
	v_mul_f32_e32 v107, v107, v91
	v_mul_f32_e32 v108, v108, v92
	v_mul_f32_e32 v109, v109, v93
	v_mul_f32_e32 v110, v110, v94
	v_mul_f32_e32 v111, v111, v95
	v_fma_f32 v104, v104, v88, v88
	v_fma_f32 v105, v105, v89, v89
	v_fma_f32 v106, v106, v90, v90
	v_fma_f32 v107, v107, v91, v91
	v_fma_f32 v108, v108, v92, v92
	v_fma_f32 v109, v109, v93, v93
	v_fma_f32 v110, v110, v94, v94
	v_fma_f32 v111, v111, v95, v95
	v_mul_f32_e32 v104, 0x3fcc422a, v104
	v_mul_f32_e32 v105, 0x3fcc422a, v105
	v_mul_f32_e32 v106, 0x3fcc422a, v106
	v_mul_f32_e32 v107, 0x3fcc422a, v107
	v_mul_f32_e32 v108, 0x3fcc422a, v108
	v_mul_f32_e32 v109, 0x3fcc422a, v109
	v_mul_f32_e32 v110, 0x3fcc422a, v110
	v_mul_f32_e32 v111, 0x3fcc422a, v111
	v_mul_f32_e32 v104, 0xbfb8aa3b, v104
	v_mul_f32_e32 v105, 0xbfb8aa3b, v105
	v_mul_f32_e32 v106, 0xbfb8aa3b, v106
	v_mul_f32_e32 v107, 0xbfb8aa3b, v107
	v_mul_f32_e32 v108, 0xbfb8aa3b, v108
	v_mul_f32_e32 v109, 0xbfb8aa3b, v109
	v_mul_f32_e32 v110, 0xbfb8aa3b, v110
	v_mul_f32_e32 v111, 0xbfb8aa3b, v111
	v_exp_f32_e32 v104, v104
	v_exp_f32_e32 v105, v105
	v_exp_f32_e32 v106, v106
	v_exp_f32_e32 v107, v107
	v_exp_f32_e32 v108, v108
	v_exp_f32_e32 v109, v109
	v_exp_f32_e32 v110, v110
	v_exp_f32_e32 v111, v111
	v_add_f32_e32 v104, 1.0, v104
	v_add_f32_e32 v105, 1.0, v105
	v_add_f32_e32 v106, 1.0, v106
	v_add_f32_e32 v107, 1.0, v107
	v_add_f32_e32 v108, 1.0, v108
	v_add_f32_e32 v109, 1.0, v109
	v_add_f32_e32 v110, 1.0, v110
	v_add_f32_e32 v111, 1.0, v111
	v_rcp_f32_e32 v104, v104
	v_rcp_f32_e32 v105, v105
	v_rcp_f32_e32 v106, v106
	v_rcp_f32_e32 v107, v107
	v_rcp_f32_e32 v108, v108
	v_rcp_f32_e32 v109, v109
	v_rcp_f32_e32 v110, v110
	v_rcp_f32_e32 v111, v111
	v_mul_f32_e32 v104, v104, v88
	v_mul_f32_e32 v105, v105, v89
	v_mul_f32_e32 v106, v106, v90
	v_mul_f32_e32 v107, v107, v91
	v_mul_f32_e32 v108, v108, v92
	v_mul_f32_e32 v109, v109, v93
	v_mul_f32_e32 v110, v110, v94
	v_mul_f32_e32 v111, v111, v95
	v_mul_f32_e32 v104, v80, v104
	v_mul_f32_e32 v105, v81, v105
	v_mul_f32_e32 v106, v82, v106
	v_mul_f32_e32 v107, v83, v107
	v_mul_f32_e32 v108, v84, v108
	v_mul_f32_e32 v109, v85, v109
	v_mul_f32_e32 v110, v86, v110
	v_mul_f32_e32 v111, v87, v111
	v_cvt_pk_bf16_f32 v112, v104, v105
	v_cvt_pk_bf16_f32 v113, v106, v107
	v_cvt_pk_bf16_f32 v114, v108, v109
	v_cvt_pk_bf16_f32 v115, v110, v111
	global_store_dwordx4 v27, v[112:115], s[24:25]
	s_add_u32 s24, s24, 0x2800
	s_addc_u32 s25, s25, 0
	global_load_dwordx4 v[32:35], v31, s[12:13]
	global_load_dwordx4 v[36:39], v31, s[12:13] offset:16
	global_load_dwordx4 v[40:43], v26, s[96:97] nt
	s_add_u32 s12, s12, 0x1000
	s_addc_u32 s13, s13, 0
	s_add_u32 s96, s96, 0x2800
	s_addc_u32 s97, s97, 0
	s_waitcnt vmcnt(10)
	v_lshlrev_b32_e32 v80, 16, v44
	v_and_b32_e32 v96, 0xffff0000, v44
	v_lshlrev_b32_e32 v81, 16, v45
	v_and_b32_e32 v97, 0xffff0000, v45
	v_lshlrev_b32_e32 v82, 16, v46
	v_and_b32_e32 v98, 0xffff0000, v46
	v_lshlrev_b32_e32 v83, 16, v47
	v_and_b32_e32 v99, 0xffff0000, v47
	v_lshlrev_b32_e32 v84, 16, v48
	v_and_b32_e32 v100, 0xffff0000, v48
	v_lshlrev_b32_e32 v85, 16, v49
	v_and_b32_e32 v101, 0xffff0000, v49
	v_lshlrev_b32_e32 v86, 16, v50
	v_and_b32_e32 v102, 0xffff0000, v50
	v_lshlrev_b32_e32 v87, 16, v51
	v_and_b32_e32 v103, 0xffff0000, v51
	v_lshlrev_b32_e32 v88, 16, v52
	v_and_b32_e32 v89, 0xffff0000, v52
	v_lshlrev_b32_e32 v90, 16, v53
	v_and_b32_e32 v91, 0xffff0000, v53
	v_lshlrev_b32_e32 v92, 16, v54
	v_and_b32_e32 v93, 0xffff0000, v54
	v_lshlrev_b32_e32 v94, 16, v55
	v_and_b32_e32 v95, 0xffff0000, v55
	v_fmac_f32_e32 v80, v96, v18
	v_fmac_f32_e32 v81, v97, v19
	v_fmac_f32_e32 v82, v98, v20
	v_fmac_f32_e32 v83, v99, v21
	v_fmac_f32_e32 v84, v100, v22
	v_fmac_f32_e32 v85, v101, v23
	v_fmac_f32_e32 v86, v102, v24
	v_fmac_f32_e32 v87, v103, v25
	v_mul_f32_e32 v104, 0x3d372713, v88
	v_mul_f32_e32 v105, 0x3d372713, v89
	v_mul_f32_e32 v106, 0x3d372713, v90
	v_mul_f32_e32 v107, 0x3d372713, v91
	v_mul_f32_e32 v108, 0x3d372713, v92
	v_mul_f32_e32 v109, 0x3d372713, v93
	v_mul_f32_e32 v110, 0x3d372713, v94
	v_mul_f32_e32 v111, 0x3d372713, v95
	v_mul_f32_e32 v104, v104, v88
	v_mul_f32_e32 v105, v105, v89
	v_mul_f32_e32 v106, v106, v90
	v_mul_f32_e32 v107, v107, v91
; __device__ __forceinline__ u32x4 pack8(const float (&f)[8]) { u32x4 o; o.x = cvt_pk_bf16(f[0], f[1]); o.y = cvt_pk_bf16(f[2], f[3]); o.z = cvt_pk_bf16(f[4], f[5]); o.w = cvt_pk_bf16(f[6], f[7]); return o; }
; __device__ __forceinline__ float gelu_tanh(float x) { return x * sigmoidf_(1.5957691216057308f * (x + 0.044715f * x * x * x)); }
; __device__ __forceinline__ void fixup_phase(KP p, int l) {
;     ...
;         for (int i = 0; i < 16; ++i) {
;             const size_t m = (size_t)(m0 + i);
;             float hl[8], pc[8], gr[8], o[8], h[8];
;             unpack8(__builtin_nontemporal_load((const u32x4*)(HLOC + m * D + c0)), hl); unpack8(__builtin_nontemporal_load((const u32x4*)(PCUM + m * D + c0)), pc);
;             bf16_t* gp = P + m * DP + C_GR + c0; unpack8(*(const u32x4*)gp, gr);
; #pragma unroll
;             for (int e = 0; e < 8; ++e) { h[e] = hl[e] + pc[e] * carry[e]; o[e] = gelu_tanh(gr[e]) * h[e]; }
;             *(u32x4*)gp = pack8(o);
	v_mul_f32_e32 v108, v108, v92
	v_mul_f32_e32 v109, v109, v93
	v_mul_f32_e32 v110, v110, v94
	v_mul_f32_e32 v111, v111, v95
	v_fma_f32 v104, v104, v88, v88
	v_fma_f32 v105, v105, v89, v89
	v_fma_f32 v106, v106, v90, v90
	v_fma_f32 v107, v107, v91, v91
	v_fma_f32 v108, v108, v92, v92
	v_fma_f32 v109, v109, v93, v93
	v_fma_f32 v110, v110, v94, v94
	v_fma_f32 v111, v111, v95, v95
	v_mul_f32_e32 v104, 0x3fcc422a, v104
	v_mul_f32_e32 v105, 0x3fcc422a, v105
	v_mul_f32_e32 v106, 0x3fcc422a, v106
	v_mul_f32_e32 v107, 0x3fcc422a, v107
	v_mul_f32_e32 v108, 0x3fcc422a, v108
	v_mul_f32_e32 v109, 0x3fcc422a, v109
	v_mul_f32_e32 v110, 0x3fcc422a, v110
	v_mul_f32_e32 v111, 0x3fcc422a, v111
	v_mul_f32_e32 v104, 0xbfb8aa3b, v104
	v_mul_f32_e32 v105, 0xbfb8aa3b, v105
	v_mul_f32_e32 v106, 0xbfb8aa3b, v106
	v_mul_f32_e32 v107, 0xbfb8aa3b, v107
	v_mul_f32_e32 v108, 0xbfb8aa3b, v108
	v_mul_f32_e32 v109, 0xbfb8aa3b, v109
	v_mul_f32_e32 v110, 0xbfb8aa3b, v110
	v_mul_f32_e32 v111, 0xbfb8aa3b, v111
	v_exp_f32_e32 v104, v104
	v_exp_f32_e32 v105, v105
	v_exp_f32_e32 v106, v106
	v_exp_f32_e32 v107, v107
	v_exp_f32_e32 v108, v108
	v_exp_f32_e32 v109, v109
	v_exp_f32_e32 v110, v110
	v_exp_f32_e32 v111, v111
	v_add_f32_e32 v104, 1.0, v104
	v_add_f32_e32 v105, 1.0, v105
	v_add_f32_e32 v106, 1.0, v106
	v_add_f32_e32 v107, 1.0, v107
	v_add_f32_e32 v108, 1.0, v108
	v_add_f32_e32 v109, 1.0, v109
	v_add_f32_e32 v110, 1.0, v110
	v_add_f32_e32 v111, 1.0, v111
	v_rcp_f32_e32 v104, v104
	v_rcp_f32_e32 v105, v105
	v_rcp_f32_e32 v106, v106
	v_rcp_f32_e32 v107, v107
	v_rcp_f32_e32 v108, v108
	v_rcp_f32_e32 v109, v109
	v_rcp_f32_e32 v110, v110
	v_rcp_f32_e32 v111, v111
	v_mul_f32_e32 v104, v104, v88
	v_mul_f32_e32 v105, v105, v89
	v_mul_f32_e32 v106, v106, v90
	v_mul_f32_e32 v107, v107, v91
	v_mul_f32_e32 v108, v108, v92
	v_mul_f32_e32 v109, v109, v93
	v_mul_f32_e32 v110, v110, v94
	v_mul_f32_e32 v111, v111, v95
	v_mul_f32_e32 v104, v80, v104
	v_mul_f32_e32 v105, v81, v105
	v_mul_f32_e32 v106, v82, v106
	v_mul_f32_e32 v107, v83, v107
	v_mul_f32_e32 v108, v84, v108
	v_mul_f32_e32 v109, v85, v109
	v_mul_f32_e32 v110, v86, v110
	v_mul_f32_e32 v111, v87, v111
	v_cvt_pk_bf16_f32 v112, v104, v105
	v_cvt_pk_bf16_f32 v113, v106, v107
	v_cvt_pk_bf16_f32 v114, v108, v109
	v_cvt_pk_bf16_f32 v115, v110, v111
	global_store_dwordx4 v27, v[112:115], s[24:25]
	s_add_u32 s24, s24, 0x2800
	s_addc_u32 s25, s25, 0
	global_load_dwordx4 v[44:47], v31, s[12:13]
	global_load_dwordx4 v[48:51], v31, s[12:13] offset:16
	global_load_dwordx4 v[52:55], v26, s[96:97] nt
	s_add_u32 s12, s12, 0x1000
	s_addc_u32 s13, s13, 0
	s_add_u32 s96, s96, 0x2800
	s_addc_u32 s97, s97, 0
	s_waitcnt vmcnt(11)
	v_lshlrev_b32_e32 v80, 16, v56
	v_and_b32_e32 v96, 0xffff0000, v56
	v_lshlrev_b32_e32 v81, 16, v57
	v_and_b32_e32 v97, 0xffff0000, v57
	v_lshlrev_b32_e32 v82, 16, v58
	v_and_b32_e32 v98, 0xffff0000, v58
	v_lshlrev_b32_e32 v83, 16, v59
	v_and_b32_e32 v99, 0xffff0000, v59
	v_lshlrev_b32_e32 v84, 16, v60
	v_and_b32_e32 v100, 0xffff0000, v60
	v_lshlrev_b32_e32 v85, 16, v61
	v_and_b32_e32 v101, 0xffff0000, v61
	v_lshlrev_b32_e32 v86, 16, v62
	v_and_b32_e32 v102, 0xffff0000, v62
	v_lshlrev_b32_e32 v87, 16, v63
	v_and_b32_e32 v103, 0xffff0000, v63
	v_lshlrev_b32_e32 v88, 16, v64
	v_and_b32_e32 v89, 0xffff0000, v64
	v_lshlrev_b32_e32 v90, 16, v65
	v_and_b32_e32 v91, 0xffff0000, v65
	v_lshlrev_b32_e32 v92, 16, v66
	v_and_b32_e32 v93, 0xffff0000, v66
	v_lshlrev_b32_e32 v94, 16, v67
	v_and_b32_e32 v95, 0xffff0000, v67
	v_fmac_f32_e32 v80, v96, v18
	v_fmac_f32_e32 v81, v97, v19
	v_fmac_f32_e32 v82, v98, v20
	v_fmac_f32_e32 v83, v99, v21
	v_fmac_f32_e32 v84, v100, v22
	v_fmac_f32_e32 v85, v101, v23
	v_fmac_f32_e32 v86, v102, v24
	v_fmac_f32_e32 v87, v103, v25
	v_mul_f32_e32 v104, 0x3d372713, v88
	v_mul_f32_e32 v105, 0x3d372713, v89
	v_mul_f32_e32 v106, 0x3d372713, v90
	v_mul_f32_e32 v107, 0x3d372713, v91
	v_mul_f32_e32 v108, 0x3d372713, v92
	v_mul_f32_e32 v109, 0x3d372713, v93
	v_mul_f32_e32 v110, 0x3d372713, v94
	v_mul_f32_e32 v111, 0x3d372713, v95
	v_mul_f32_e32 v104, v104, v88
	v_mul_f32_e32 v105, v105, v89
	v_mul_f32_e32 v106, v106, v90
	v_mul_f32_e32 v107, v107, v91
	v_mul_f32_e32 v108, v108, v92
	v_mul_f32_e32 v109, v109, v93
	v_mul_f32_e32 v110, v110, v94
	v_mul_f32_e32 v111, v111, v95
	v_fma_f32 v104, v104, v88, v88
	v_fma_f32 v105, v105, v89, v89
	v_fma_f32 v106, v106, v90, v90
	v_fma_f32 v107, v107, v91, v91
	v_fma_f32 v108, v108, v92, v92
	v_fma_f32 v109, v109, v93, v93
	v_fma_f32 v110, v110, v94, v94
	v_fma_f32 v111, v111, v95, v95
	v_mul_f32_e32 v104, 0x3fcc422a, v104
	v_mul_f32_e32 v105, 0x3fcc422a, v105
	v_mul_f32_e32 v106, 0x3fcc422a, v106
	v_mul_f32_e32 v107, 0x3fcc422a, v107
	v_mul_f32_e32 v108, 0x3fcc422a, v108
	v_mul_f32_e32 v109, 0x3fcc422a, v109
	v_mul_f32_e32 v110, 0x3fcc422a, v110
	v_mul_f32_e32 v111, 0x3fcc422a, v111
	v_mul_f32_e32 v104, 0xbfb8aa3b, v104
	v_mul_f32_e32 v105, 0xbfb8aa3b, v105
	v_mul_f32_e32 v106, 0xbfb8aa3b, v106
	v_mul_f32_e32 v107, 0xbfb8aa3b, v107
	v_mul_f32_e32 v108, 0xbfb8aa3b, v108
	v_mul_f32_e32 v109, 0xbfb8aa3b, v109
	v_mul_f32_e32 v110, 0xbfb8aa3b, v110
	v_mul_f32_e32 v111, 0xbfb8aa3b, v111
	v_exp_f32_e32 v104, v104
	v_exp_f32_e32 v105, v105
	v_exp_f32_e32 v106, v106
	v_exp_f32_e32 v107, v107
	v_exp_f32_e32 v108, v108
	v_exp_f32_e32 v109, v109
	v_exp_f32_e32 v110, v110
	v_exp_f32_e32 v111, v111
	v_add_f32_e32 v104, 1.0, v104
	v_add_f32_e32 v105, 1.0, v105
	v_add_f32_e32 v106, 1.0, v106
	v_add_f32_e32 v107, 1.0, v107
	v_add_f32_e32 v108, 1.0, v108
	v_add_f32_e32 v109, 1.0, v109
	v_add_f32_e32 v110, 1.0, v110
	v_add_f32_e32 v111, 1.0, v111
	v_rcp_f32_e32 v104, v104
	v_rcp_f32_e32 v105, v105
	v_rcp_f32_e32 v106, v106
	v_rcp_f32_e32 v107, v107
	v_rcp_f32_e32 v108, v108
	v_rcp_f32_e32 v109, v109
	v_rcp_f32_e32 v110, v110
	v_rcp_f32_e32 v111, v111
	v_mul_f32_e32 v104, v104, v88
	v_mul_f32_e32 v105, v105, v89
	v_mul_f32_e32 v106, v106, v90
	v_mul_f32_e32 v107, v107, v91
	v_mul_f32_e32 v108, v108, v92
	v_mul_f32_e32 v109, v109, v93
	v_mul_f32_e32 v110, v110, v94
	v_mul_f32_e32 v111, v111, v95
	v_mul_f32_e32 v104, v80, v104
	v_mul_f32_e32 v105, v81, v105
	v_mul_f32_e32 v106, v82, v106
	v_mul_f32_e32 v107, v83, v107
	v_mul_f32_e32 v108, v84, v108
	v_mul_f32_e32 v109, v85, v109
	v_mul_f32_e32 v110, v86, v110
	v_mul_f32_e32 v111, v87, v111
	v_cvt_pk_bf16_f32 v112, v104, v105
	v_cvt_pk_bf16_f32 v113, v106, v107
	v_cvt_pk_bf16_f32 v114, v108, v109
	v_cvt_pk_bf16_f32 v115, v110, v111
	global_store_dwordx4 v27, v[112:115], s[24:25]
	s_add_u32 s24, s24, 0x2800
	s_addc_u32 s25, s25, 0
	global_load_dwordx4 v[56:59], v31, s[12:13]
	global_load_dwordx4 v[60:63], v31, s[12:13] offset:16
	global_load_dwordx4 v[64:67], v26, s[96:97] nt
	s_add_u32 s12, s12, 0x1000
	s_addc_u32 s13, s13, 0
	s_add_u32 s96, s96, 0x2800
	s_addc_u32 s97, s97, 0
	s_waitcnt vmcnt(12)
; __device__ __forceinline__ u32x4 pack8(const float (&f)[8]) { u32x4 o; o.x = cvt_pk_bf16(f[0], f[1]); o.y = cvt_pk_bf16(f[2], f[3]); o.z = cvt_pk_bf16(f[4], f[5]); o.w = cvt_pk_bf16(f[6], f[7]); return o; }
; __device__ __forceinline__ float sigmoidf_(float x) { return __builtin_amdgcn_rcpf(1.0f + __expf(-x)); }
; __device__ __forceinline__ float gelu_tanh(float x) { return x * sigmoidf_(1.5957691216057308f * (x + 0.044715f * x * x * x)); }
; __device__ __forceinline__ void fixup_phase(KP p, int l) {
;     ...
;         for (int i = 0; i < 16; ++i) {
;             const size_t m = (size_t)(m0 + i);
;             float hl[8], pc[8], gr[8], o[8], h[8];
;             unpack8(__builtin_nontemporal_load((const u32x4*)(HLOC + m * D + c0)), hl); unpack8(__builtin_nontemporal_load((const u32x4*)(PCUM + m * D + c0)), pc);
;             bf16_t* gp = P + m * DP + C_GR + c0; unpack8(*(const u32x4*)gp, gr);
; #pragma unroll
;             for (int e = 0; e < 8; ++e) { h[e] = hl[e] + pc[e] * carry[e]; o[e] = gelu_tanh(gr[e]) * h[e]; }
;             *(u32x4*)gp = pack8(o);
	v_lshlrev_b32_e32 v80, 16, v68
	v_and_b32_e32 v96, 0xffff0000, v68
	v_lshlrev_b32_e32 v81, 16, v69
	v_and_b32_e32 v97, 0xffff0000, v69
	v_lshlrev_b32_e32 v82, 16, v70
	v_and_b32_e32 v98, 0xffff0000, v70
	v_lshlrev_b32_e32 v83, 16, v71
	v_and_b32_e32 v99, 0xffff0000, v71
	v_lshlrev_b32_e32 v84, 16, v72
	v_and_b32_e32 v100, 0xffff0000, v72
	v_lshlrev_b32_e32 v85, 16, v73
	v_and_b32_e32 v101, 0xffff0000, v73
	v_lshlrev_b32_e32 v86, 16, v74
	v_and_b32_e32 v102, 0xffff0000, v74
	v_lshlrev_b32_e32 v87, 16, v75
	v_and_b32_e32 v103, 0xffff0000, v75
	v_lshlrev_b32_e32 v88, 16, v76
	v_and_b32_e32 v89, 0xffff0000, v76
	v_lshlrev_b32_e32 v90, 16, v77
	v_and_b32_e32 v91, 0xffff0000, v77
	v_lshlrev_b32_e32 v92, 16, v78
	v_and_b32_e32 v93, 0xffff0000, v78
	v_lshlrev_b32_e32 v94, 16, v79
	v_and_b32_e32 v95, 0xffff0000, v79
	v_fmac_f32_e32 v80, v96, v18
	v_fmac_f32_e32 v81, v97, v19
	v_fmac_f32_e32 v82, v98, v20
	v_fmac_f32_e32 v83, v99, v21
	v_fmac_f32_e32 v84, v100, v22
	v_fmac_f32_e32 v85, v101, v23
	v_fmac_f32_e32 v86, v102, v24
	v_fmac_f32_e32 v87, v103, v25
	v_mul_f32_e32 v104, 0x3d372713, v88
	v_mul_f32_e32 v105, 0x3d372713, v89
	v_mul_f32_e32 v106, 0x3d372713, v90
	v_mul_f32_e32 v107, 0x3d372713, v91
	v_mul_f32_e32 v108, 0x3d372713, v92
	v_mul_f32_e32 v109, 0x3d372713, v93
	v_mul_f32_e32 v110, 0x3d372713, v94
	v_mul_f32_e32 v111, 0x3d372713, v95
	v_mul_f32_e32 v104, v104, v88
	v_mul_f32_e32 v105, v105, v89
	v_mul_f32_e32 v106, v106, v90
	v_mul_f32_e32 v107, v107, v91
	v_mul_f32_e32 v108, v108, v92
	v_mul_f32_e32 v109, v109, v93
	v_mul_f32_e32 v110, v110, v94
	v_mul_f32_e32 v111, v111, v95
	v_fma_f32 v104, v104, v88, v88
	v_fma_f32 v105, v105, v89, v89
	v_fma_f32 v106, v106, v90, v90
	v_fma_f32 v107, v107, v91, v91
	v_fma_f32 v108, v108, v92, v92
	v_fma_f32 v109, v109, v93, v93
	v_fma_f32 v110, v110, v94, v94
	v_fma_f32 v111, v111, v95, v95
	v_mul_f32_e32 v104, 0x3fcc422a, v104
	v_mul_f32_e32 v105, 0x3fcc422a, v105
	v_mul_f32_e32 v106, 0x3fcc422a, v106
	v_mul_f32_e32 v107, 0x3fcc422a, v107
	v_mul_f32_e32 v108, 0x3fcc422a, v108
	v_mul_f32_e32 v109, 0x3fcc422a, v109
	v_mul_f32_e32 v110, 0x3fcc422a, v110
	v_mul_f32_e32 v111, 0x3fcc422a, v111
	v_mul_f32_e32 v104, 0xbfb8aa3b, v104
	v_mul_f32_e32 v105, 0xbfb8aa3b, v105
	v_mul_f32_e32 v106, 0xbfb8aa3b, v106
	v_mul_f32_e32 v107, 0xbfb8aa3b, v107
	v_mul_f32_e32 v108, 0xbfb8aa3b, v108
	v_mul_f32_e32 v109, 0xbfb8aa3b, v109
	v_mul_f32_e32 v110, 0xbfb8aa3b, v110
	v_mul_f32_e32 v111, 0xbfb8aa3b, v111
	v_exp_f32_e32 v104, v104
	v_exp_f32_e32 v105, v105
	v_exp_f32_e32 v106, v106
	v_exp_f32_e32 v107, v107
	v_exp_f32_e32 v108, v108
	v_exp_f32_e32 v109, v109
	v_exp_f32_e32 v110, v110
	v_exp_f32_e32 v111, v111
	v_add_f32_e32 v104, 1.0, v104
	v_add_f32_e32 v105, 1.0, v105
	v_add_f32_e32 v106, 1.0, v106
	v_add_f32_e32 v107, 1.0, v107
	v_add_f32_e32 v108, 1.0, v108
	v_add_f32_e32 v109, 1.0, v109
	v_add_f32_e32 v110, 1.0, v110
	v_add_f32_e32 v111, 1.0, v111
	v_rcp_f32_e32 v104, v104
	v_rcp_f32_e32 v105, v105
	v_rcp_f32_e32 v106, v106
	v_rcp_f32_e32 v107, v107
	v_rcp_f32_e32 v108, v108
	v_rcp_f32_e32 v109, v109
	v_rcp_f32_e32 v110, v110
	v_rcp_f32_e32 v111, v111
	v_mul_f32_e32 v104, v104, v88
	v_mul_f32_e32 v105, v105, v89
	v_mul_f32_e32 v106, v106, v90
	v_mul_f32_e32 v107, v107, v91
	v_mul_f32_e32 v108, v108, v92
	v_mul_f32_e32 v109, v109, v93
	v_mul_f32_e32 v110, v110, v94
	v_mul_f32_e32 v111, v111, v95
	v_mul_f32_e32 v104, v80, v104
	v_mul_f32_e32 v105, v81, v105
	v_mul_f32_e32 v106, v82, v106
	v_mul_f32_e32 v107, v83, v107
	v_mul_f32_e32 v108, v84, v108
	v_mul_f32_e32 v109, v85, v109
	v_mul_f32_e32 v110, v86, v110
	v_mul_f32_e32 v111, v87, v111
	v_cvt_pk_bf16_f32 v112, v104, v105
	v_cvt_pk_bf16_f32 v113, v106, v107
	v_cvt_pk_bf16_f32 v114, v108, v109
	v_cvt_pk_bf16_f32 v115, v110, v111
	global_store_dwordx4 v27, v[112:115], s[24:25]
	s_add_u32 s24, s24, 0x2800
	s_addc_u32 s25, s25, 0
	global_load_dwordx4 v[68:71], v31, s[12:13]
	global_load_dwordx4 v[72:75], v31, s[12:13] offset:16
	global_load_dwordx4 v[76:79], v26, s[96:97] nt
	s_add_u32 s12, s12, 0x1000
	s_addc_u32 s13, s13, 0
	s_add_u32 s96, s96, 0x2800
	s_addc_u32 s97, s97, 0
	s_waitcnt vmcnt(12)
	v_lshlrev_b32_e32 v80, 16, v32
	v_and_b32_e32 v96, 0xffff0000, v32
	v_lshlrev_b32_e32 v81, 16, v33
	v_and_b32_e32 v97, 0xffff0000, v33
	v_lshlrev_b32_e32 v82, 16, v34
	v_and_b32_e32 v98, 0xffff0000, v34
	v_lshlrev_b32_e32 v83, 16, v35
	v_and_b32_e32 v99, 0xffff0000, v35
	v_lshlrev_b32_e32 v84, 16, v36
	v_and_b32_e32 v100, 0xffff0000, v36
	v_lshlrev_b32_e32 v85, 16, v37
	v_and_b32_e32 v101, 0xffff0000, v37
	v_lshlrev_b32_e32 v86, 16, v38
	v_and_b32_e32 v102, 0xffff0000, v38
	v_lshlrev_b32_e32 v87, 16, v39
	v_and_b32_e32 v103, 0xffff0000, v39
	v_lshlrev_b32_e32 v88, 16, v40
	v_and_b32_e32 v89, 0xffff0000, v40
	v_lshlrev_b32_e32 v90, 16, v41
	v_and_b32_e32 v91, 0xffff0000, v41
	v_lshlrev_b32_e32 v92, 16, v42
	v_and_b32_e32 v93, 0xffff0000, v42
	v_lshlrev_b32_e32 v94, 16, v43
	v_and_b32_e32 v95, 0xffff0000, v43
	v_fmac_f32_e32 v80, v96, v18
	v_fmac_f32_e32 v81, v97, v19
	v_fmac_f32_e32 v82, v98, v20
	v_fmac_f32_e32 v83, v99, v21
	v_fmac_f32_e32 v84, v100, v22
	v_fmac_f32_e32 v85, v101, v23
	v_fmac_f32_e32 v86, v102, v24
	v_fmac_f32_e32 v87, v103, v25
	v_mul_f32_e32 v104, 0x3d372713, v88
	v_mul_f32_e32 v105, 0x3d372713, v89
	v_mul_f32_e32 v106, 0x3d372713, v90
	v_mul_f32_e32 v107, 0x3d372713, v91
	v_mul_f32_e32 v108, 0x3d372713, v92
	v_mul_f32_e32 v109, 0x3d372713, v93
	v_mul_f32_e32 v110, 0x3d372713, v94
	v_mul_f32_e32 v111, 0x3d372713, v95
	v_mul_f32_e32 v104, v104, v88
	v_mul_f32_e32 v105, v105, v89
	v_mul_f32_e32 v106, v106, v90
	v_mul_f32_e32 v107, v107, v91
; __device__ __forceinline__ u32x4 pack8(const float (&f)[8]) { u32x4 o; o.x = cvt_pk_bf16(f[0], f[1]); o.y = cvt_pk_bf16(f[2], f[3]); o.z = cvt_pk_bf16(f[4], f[5]); o.w = cvt_pk_bf16(f[6], f[7]); return o; }
; __device__ __forceinline__ float sigmoidf_(float x) { return __builtin_amdgcn_rcpf(1.0f + __expf(-x)); }
; __device__ __forceinline__ float gelu_tanh(float x) { return x * sigmoidf_(1.5957691216057308f * (x + 0.044715f * x * x * x)); }
; __device__ __forceinline__ void fixup_phase(KP p, int l) {
;     ...
;         for (int i = 0; i < 16; ++i) {
;             const size_t m = (size_t)(m0 + i);
;             float hl[8], pc[8], gr[8], o[8], h[8];
;             unpack8(__builtin_nontemporal_load((const u32x4*)(HLOC + m * D + c0)), hl); unpack8(__builtin_nontemporal_load((const u32x4*)(PCUM + m * D + c0)), pc);
;             bf16_t* gp = P + m * DP + C_GR + c0; unpack8(*(const u32x4*)gp, gr);
; #pragma unroll
;             for (int e = 0; e < 8; ++e) { h[e] = hl[e] + pc[e] * carry[e]; o[e] = gelu_tanh(gr[e]) * h[e]; }
;             *(u32x4*)gp = pack8(o);
	v_mul_f32_e32 v108, v108, v92
	v_mul_f32_e32 v109, v109, v93
	v_mul_f32_e32 v110, v110, v94
	v_mul_f32_e32 v111, v111, v95
	v_fma_f32 v104, v104, v88, v88
	v_fma_f32 v105, v105, v89, v89
	v_fma_f32 v106, v106, v90, v90
	v_fma_f32 v107, v107, v91, v91
	v_fma_f32 v108, v108, v92, v92
	v_fma_f32 v109, v109, v93, v93
	v_fma_f32 v110, v110, v94, v94
	v_fma_f32 v111, v111, v95, v95
	v_mul_f32_e32 v104, 0x3fcc422a, v104
	v_mul_f32_e32 v105, 0x3fcc422a, v105
	v_mul_f32_e32 v106, 0x3fcc422a, v106
	v_mul_f32_e32 v107, 0x3fcc422a, v107
	v_mul_f32_e32 v108, 0x3fcc422a, v108
	v_mul_f32_e32 v109, 0x3fcc422a, v109
	v_mul_f32_e32 v110, 0x3fcc422a, v110
	v_mul_f32_e32 v111, 0x3fcc422a, v111
	v_mul_f32_e32 v104, 0xbfb8aa3b, v104
	v_mul_f32_e32 v105, 0xbfb8aa3b, v105
	v_mul_f32_e32 v106, 0xbfb8aa3b, v106
	v_mul_f32_e32 v107, 0xbfb8aa3b, v107
	v_mul_f32_e32 v108, 0xbfb8aa3b, v108
	v_mul_f32_e32 v109, 0xbfb8aa3b, v109
	v_mul_f32_e32 v110, 0xbfb8aa3b, v110
	v_mul_f32_e32 v111, 0xbfb8aa3b, v111
	v_exp_f32_e32 v104, v104
	v_exp_f32_e32 v105, v105
	v_exp_f32_e32 v106, v106
	v_exp_f32_e32 v107, v107
	v_exp_f32_e32 v108, v108
	v_exp_f32_e32 v109, v109
	v_exp_f32_e32 v110, v110
	v_exp_f32_e32 v111, v111
	v_add_f32_e32 v104, 1.0, v104
	v_add_f32_e32 v105, 1.0, v105
	v_add_f32_e32 v106, 1.0, v106
	v_add_f32_e32 v107, 1.0, v107
	v_add_f32_e32 v108, 1.0, v108
	v_add_f32_e32 v109, 1.0, v109
	v_add_f32_e32 v110, 1.0, v110
	v_add_f32_e32 v111, 1.0, v111
	v_rcp_f32_e32 v104, v104
	v_rcp_f32_e32 v105, v105
	v_rcp_f32_e32 v106, v106
	v_rcp_f32_e32 v107, v107
	v_rcp_f32_e32 v108, v108
	v_rcp_f32_e32 v109, v109
	v_rcp_f32_e32 v110, v110
	v_rcp_f32_e32 v111, v111
	v_mul_f32_e32 v104, v104, v88
	v_mul_f32_e32 v105, v105, v89
	v_mul_f32_e32 v106, v106, v90
	v_mul_f32_e32 v107, v107, v91
	v_mul_f32_e32 v108, v108, v92
	v_mul_f32_e32 v109, v109, v93
	v_mul_f32_e32 v110, v110, v94
	v_mul_f32_e32 v111, v111, v95
	v_mul_f32_e32 v104, v80, v104
	v_mul_f32_e32 v105, v81, v105
	v_mul_f32_e32 v106, v82, v106
	v_mul_f32_e32 v107, v83, v107
	v_mul_f32_e32 v108, v84, v108
	v_mul_f32_e32 v109, v85, v109
	v_mul_f32_e32 v110, v86, v110
	v_mul_f32_e32 v111, v87, v111
	v_cvt_pk_bf16_f32 v112, v104, v105
	v_cvt_pk_bf16_f32 v113, v106, v107
	v_cvt_pk_bf16_f32 v114, v108, v109
	v_cvt_pk_bf16_f32 v115, v110, v111
	global_store_dwordx4 v27, v[112:115], s[24:25]
	s_add_u32 s24, s24, 0x2800
	s_addc_u32 s25, s25, 0
	global_load_dwordx4 v[32:35], v31, s[12:13]
	global_load_dwordx4 v[36:39], v31, s[12:13] offset:16
	global_load_dwordx4 v[40:43], v26, s[96:97] nt
	s_add_u32 s12, s12, 0x1000
	s_addc_u32 s13, s13, 0
	s_add_u32 s96, s96, 0x2800
	s_addc_u32 s97, s97, 0
	s_waitcnt vmcnt(12)
	v_lshlrev_b32_e32 v80, 16, v44
	v_and_b32_e32 v96, 0xffff0000, v44
	v_lshlrev_b32_e32 v81, 16, v45
	v_and_b32_e32 v97, 0xffff0000, v45
	v_lshlrev_b32_e32 v82, 16, v46
	v_and_b32_e32 v98, 0xffff0000, v46
	v_lshlrev_b32_e32 v83, 16, v47
	v_and_b32_e32 v99, 0xffff0000, v47
	v_lshlrev_b32_e32 v84, 16, v48
	v_and_b32_e32 v100, 0xffff0000, v48
	v_lshlrev_b32_e32 v85, 16, v49
	v_and_b32_e32 v101, 0xffff0000, v49
	v_lshlrev_b32_e32 v86, 16, v50
	v_and_b32_e32 v102, 0xffff0000, v50
	v_lshlrev_b32_e32 v87, 16, v51
	v_and_b32_e32 v103, 0xffff0000, v51
	v_lshlrev_b32_e32 v88, 16, v52
	v_and_b32_e32 v89, 0xffff0000, v52
	v_lshlrev_b32_e32 v90, 16, v53
	v_and_b32_e32 v91, 0xffff0000, v53
	v_lshlrev_b32_e32 v92, 16, v54
	v_and_b32_e32 v93, 0xffff0000, v54
	v_lshlrev_b32_e32 v94, 16, v55
	v_and_b32_e32 v95, 0xffff0000, v55
	v_fmac_f32_e32 v80, v96, v18
	v_fmac_f32_e32 v81, v97, v19
	v_fmac_f32_e32 v82, v98, v20
	v_fmac_f32_e32 v83, v99, v21
	v_fmac_f32_e32 v84, v100, v22
	v_fmac_f32_e32 v85, v101, v23
	v_fmac_f32_e32 v86, v102, v24
	v_fmac_f32_e32 v87, v103, v25
	v_mul_f32_e32 v104, 0x3d372713, v88
	v_mul_f32_e32 v105, 0x3d372713, v89
	v_mul_f32_e32 v106, 0x3d372713, v90
	v_mul_f32_e32 v107, 0x3d372713, v91
	v_mul_f32_e32 v108, 0x3d372713, v92
	v_mul_f32_e32 v109, 0x3d372713, v93
	v_mul_f32_e32 v110, 0x3d372713, v94
	v_mul_f32_e32 v111, 0x3d372713, v95
	v_mul_f32_e32 v104, v104, v88
	v_mul_f32_e32 v105, v105, v89
	v_mul_f32_e32 v106, v106, v90
	v_mul_f32_e32 v107, v107, v91
	v_mul_f32_e32 v108, v108, v92
	v_mul_f32_e32 v109, v109, v93
	v_mul_f32_e32 v110, v110, v94
	v_mul_f32_e32 v111, v111, v95
	v_fma_f32 v104, v104, v88, v88
	v_fma_f32 v105, v105, v89, v89
	v_fma_f32 v106, v106, v90, v90
	v_fma_f32 v107, v107, v91, v91
	v_fma_f32 v108, v108, v92, v92
	v_fma_f32 v109, v109, v93, v93
	v_fma_f32 v110, v110, v94, v94
	v_fma_f32 v111, v111, v95, v95
	v_mul_f32_e32 v104, 0x3fcc422a, v104
	v_mul_f32_e32 v105, 0x3fcc422a, v105
	v_mul_f32_e32 v106, 0x3fcc422a, v106
	v_mul_f32_e32 v107, 0x3fcc422a, v107
	v_mul_f32_e32 v108, 0x3fcc422a, v108
	v_mul_f32_e32 v109, 0x3fcc422a, v109
	v_mul_f32_e32 v110, 0x3fcc422a, v110
	v_mul_f32_e32 v111, 0x3fcc422a, v111
	v_mul_f32_e32 v104, 0xbfb8aa3b, v104
	v_mul_f32_e32 v105, 0xbfb8aa3b, v105
	v_mul_f32_e32 v106, 0xbfb8aa3b, v106
	v_mul_f32_e32 v107, 0xbfb8aa3b, v107
	v_mul_f32_e32 v108, 0xbfb8aa3b, v108
	v_mul_f32_e32 v109, 0xbfb8aa3b, v109
	v_mul_f32_e32 v110, 0xbfb8aa3b, v110
	v_mul_f32_e32 v111, 0xbfb8aa3b, v111
	v_exp_f32_e32 v104, v104
	v_exp_f32_e32 v105, v105
	v_exp_f32_e32 v106, v106
	v_exp_f32_e32 v107, v107
	v_exp_f32_e32 v108, v108
	v_exp_f32_e32 v109, v109
	v_exp_f32_e32 v110, v110
	v_exp_f32_e32 v111, v111
	v_add_f32_e32 v104, 1.0, v104
	v_add_f32_e32 v105, 1.0, v105
	v_add_f32_e32 v106, 1.0, v106
	v_add_f32_e32 v107, 1.0, v107
	v_add_f32_e32 v108, 1.0, v108
	v_add_f32_e32 v109, 1.0, v109
	v_add_f32_e32 v110, 1.0, v110
	v_add_f32_e32 v111, 1.0, v111
	v_rcp_f32_e32 v104, v104
	v_rcp_f32_e32 v105, v105
	v_rcp_f32_e32 v106, v106
	v_rcp_f32_e32 v107, v107
	v_rcp_f32_e32 v108, v108
	v_rcp_f32_e32 v109, v109
	v_rcp_f32_e32 v110, v110
	v_rcp_f32_e32 v111, v111
	v_mul_f32_e32 v104, v104, v88
	v_mul_f32_e32 v105, v105, v89
	v_mul_f32_e32 v106, v106, v90
	v_mul_f32_e32 v107, v107, v91
	v_mul_f32_e32 v108, v108, v92
	v_mul_f32_e32 v109, v109, v93
	v_mul_f32_e32 v110, v110, v94
	v_mul_f32_e32 v111, v111, v95
	v_mul_f32_e32 v104, v80, v104
	v_mul_f32_e32 v105, v81, v105
	v_mul_f32_e32 v106, v82, v106
	v_mul_f32_e32 v107, v83, v107
	v_mul_f32_e32 v108, v84, v108
	v_mul_f32_e32 v109, v85, v109
	v_mul_f32_e32 v110, v86, v110
	v_mul_f32_e32 v111, v87, v111
	v_cvt_pk_bf16_f32 v112, v104, v105
	v_cvt_pk_bf16_f32 v113, v106, v107
	v_cvt_pk_bf16_f32 v114, v108, v109
	v_cvt_pk_bf16_f32 v115, v110, v111
	global_store_dwordx4 v27, v[112:115], s[24:25]
	s_add_u32 s24, s24, 0x2800
	s_addc_u32 s25, s25, 0
	global_load_dwordx4 v[44:47], v31, s[12:13]
	global_load_dwordx4 v[48:51], v31, s[12:13] offset:16
	global_load_dwordx4 v[52:55], v26, s[96:97] nt
	s_add_u32 s12, s12, 0x1000
	s_addc_u32 s13, s13, 0
	s_add_u32 s96, s96, 0x2800
	s_addc_u32 s97, s97, 0
	s_waitcnt vmcnt(12)
; __device__ __forceinline__ u32x4 pack8(const float (&f)[8]) { u32x4 o; o.x = cvt_pk_bf16(f[0], f[1]); o.y = cvt_pk_bf16(f[2], f[3]); o.z = cvt_pk_bf16(f[4], f[5]); o.w = cvt_pk_bf16(f[6], f[7]); return o; }
; __device__ __forceinline__ float sigmoidf_(float x) { return __builtin_amdgcn_rcpf(1.0f + __expf(-x)); }
; __device__ __forceinline__ float gelu_tanh(float x) { return x * sigmoidf_(1.5957691216057308f * (x + 0.044715f * x * x * x)); }
; __device__ __forceinline__ void fixup_phase(KP p, int l) {
;     ...
;         for (int i = 0; i < 16; ++i) {
;             const size_t m = (size_t)(m0 + i);
;             float hl[8], pc[8], gr[8], o[8], h[8];
;             unpack8(__builtin_nontemporal_load((const u32x4*)(HLOC + m * D + c0)), hl); unpack8(__builtin_nontemporal_load((const u32x4*)(PCUM + m * D + c0)), pc);
;             bf16_t* gp = P + m * DP + C_GR + c0; unpack8(*(const u32x4*)gp, gr);
; #pragma unroll
;             for (int e = 0; e < 8; ++e) { h[e] = hl[e] + pc[e] * carry[e]; o[e] = gelu_tanh(gr[e]) * h[e]; }
;             *(u32x4*)gp = pack8(o);
	v_lshlrev_b32_e32 v80, 16, v56
	v_and_b32_e32 v96, 0xffff0000, v56
	v_lshlrev_b32_e32 v81, 16, v57
	v_and_b32_e32 v97, 0xffff0000, v57
	v_lshlrev_b32_e32 v82, 16, v58
	v_and_b32_e32 v98, 0xffff0000, v58
	v_lshlrev_b32_e32 v83, 16, v59
	v_and_b32_e32 v99, 0xffff0000, v59
	v_lshlrev_b32_e32 v84, 16, v60
	v_and_b32_e32 v100, 0xffff0000, v60
	v_lshlrev_b32_e32 v85, 16, v61
	v_and_b32_e32 v101, 0xffff0000, v61
	v_lshlrev_b32_e32 v86, 16, v62
	v_and_b32_e32 v102, 0xffff0000, v62
	v_lshlrev_b32_e32 v87, 16, v63
	v_and_b32_e32 v103, 0xffff0000, v63
	v_lshlrev_b32_e32 v88, 16, v64
	v_and_b32_e32 v89, 0xffff0000, v64
	v_lshlrev_b32_e32 v90, 16, v65
	v_and_b32_e32 v91, 0xffff0000, v65
	v_lshlrev_b32_e32 v92, 16, v66
	v_and_b32_e32 v93, 0xffff0000, v66
	v_lshlrev_b32_e32 v94, 16, v67
	v_and_b32_e32 v95, 0xffff0000, v67
	v_fmac_f32_e32 v80, v96, v18
	v_fmac_f32_e32 v81, v97, v19
	v_fmac_f32_e32 v82, v98, v20
	v_fmac_f32_e32 v83, v99, v21
	v_fmac_f32_e32 v84, v100, v22
	v_fmac_f32_e32 v85, v101, v23
	v_fmac_f32_e32 v86, v102, v24
	v_fmac_f32_e32 v87, v103, v25
	v_mul_f32_e32 v104, 0x3d372713, v88
	v_mul_f32_e32 v105, 0x3d372713, v89
	v_mul_f32_e32 v106, 0x3d372713, v90
	v_mul_f32_e32 v107, 0x3d372713, v91
	v_mul_f32_e32 v108, 0x3d372713, v92
	v_mul_f32_e32 v109, 0x3d372713, v93
	v_mul_f32_e32 v110, 0x3d372713, v94
	v_mul_f32_e32 v111, 0x3d372713, v95
	v_mul_f32_e32 v104, v104, v88
	v_mul_f32_e32 v105, v105, v89
	v_mul_f32_e32 v106, v106, v90
	v_mul_f32_e32 v107, v107, v91
	v_mul_f32_e32 v108, v108, v92
	v_mul_f32_e32 v109, v109, v93
	v_mul_f32_e32 v110, v110, v94
	v_mul_f32_e32 v111, v111, v95
	v_fma_f32 v104, v104, v88, v88
	v_fma_f32 v105, v105, v89, v89
	v_fma_f32 v106, v106, v90, v90
	v_fma_f32 v107, v107, v91, v91
	v_fma_f32 v108, v108, v92, v92
	v_fma_f32 v109, v109, v93, v93
	v_fma_f32 v110, v110, v94, v94
	v_fma_f32 v111, v111, v95, v95
	v_mul_f32_e32 v104, 0x3fcc422a, v104
	v_mul_f32_e32 v105, 0x3fcc422a, v105
	v_mul_f32_e32 v106, 0x3fcc422a, v106
	v_mul_f32_e32 v107, 0x3fcc422a, v107
	v_mul_f32_e32 v108, 0x3fcc422a, v108
	v_mul_f32_e32 v109, 0x3fcc422a, v109
	v_mul_f32_e32 v110, 0x3fcc422a, v110
	v_mul_f32_e32 v111, 0x3fcc422a, v111
	v_mul_f32_e32 v104, 0xbfb8aa3b, v104
	v_mul_f32_e32 v105, 0xbfb8aa3b, v105
	v_mul_f32_e32 v106, 0xbfb8aa3b, v106
	v_mul_f32_e32 v107, 0xbfb8aa3b, v107
	v_mul_f32_e32 v108, 0xbfb8aa3b, v108
	v_mul_f32_e32 v109, 0xbfb8aa3b, v109
	v_mul_f32_e32 v110, 0xbfb8aa3b, v110
	v_mul_f32_e32 v111, 0xbfb8aa3b, v111
	v_exp_f32_e32 v104, v104
	v_exp_f32_e32 v105, v105
	v_exp_f32_e32 v106, v106
	v_exp_f32_e32 v107, v107
	v_exp_f32_e32 v108, v108
	v_exp_f32_e32 v109, v109
	v_exp_f32_e32 v110, v110
	v_exp_f32_e32 v111, v111
	v_add_f32_e32 v104, 1.0, v104
	v_add_f32_e32 v105, 1.0, v105
	v_add_f32_e32 v106, 1.0, v106
	v_add_f32_e32 v107, 1.0, v107
	v_add_f32_e32 v108, 1.0, v108
	v_add_f32_e32 v109, 1.0, v109
	v_add_f32_e32 v110, 1.0, v110
	v_add_f32_e32 v111, 1.0, v111
	v_rcp_f32_e32 v104, v104
	v_rcp_f32_e32 v105, v105
	v_rcp_f32_e32 v106, v106
	v_rcp_f32_e32 v107, v107
	v_rcp_f32_e32 v108, v108
	v_rcp_f32_e32 v109, v109
	v_rcp_f32_e32 v110, v110
	v_rcp_f32_e32 v111, v111
	v_mul_f32_e32 v104, v104, v88
	v_mul_f32_e32 v105, v105, v89
	v_mul_f32_e32 v106, v106, v90
	v_mul_f32_e32 v107, v107, v91
	v_mul_f32_e32 v108, v108, v92
	v_mul_f32_e32 v109, v109, v93
	v_mul_f32_e32 v110, v110, v94
	v_mul_f32_e32 v111, v111, v95
	v_mul_f32_e32 v104, v80, v104
	v_mul_f32_e32 v105, v81, v105
	v_mul_f32_e32 v106, v82, v106
	v_mul_f32_e32 v107, v83, v107
	v_mul_f32_e32 v108, v84, v108
	v_mul_f32_e32 v109, v85, v109
	v_mul_f32_e32 v110, v86, v110
	v_mul_f32_e32 v111, v87, v111
	v_cvt_pk_bf16_f32 v112, v104, v105
	v_cvt_pk_bf16_f32 v113, v106, v107
	v_cvt_pk_bf16_f32 v114, v108, v109
	v_cvt_pk_bf16_f32 v115, v110, v111
	global_store_dwordx4 v27, v[112:115], s[24:25]
	s_add_u32 s24, s24, 0x2800
	s_addc_u32 s25, s25, 0
	global_load_dwordx4 v[56:59], v31, s[12:13]
	global_load_dwordx4 v[60:63], v31, s[12:13] offset:16
	global_load_dwordx4 v[64:67], v26, s[96:97] nt
	s_add_u32 s12, s12, 0x1000
	s_addc_u32 s13, s13, 0
	s_add_u32 s96, s96, 0x2800
	s_addc_u32 s97, s97, 0
	s_waitcnt vmcnt(12)
	v_lshlrev_b32_e32 v80, 16, v68
	v_and_b32_e32 v96, 0xffff0000, v68
	v_lshlrev_b32_e32 v81, 16, v69
	v_and_b32_e32 v97, 0xffff0000, v69
	v_lshlrev_b32_e32 v82, 16, v70
	v_and_b32_e32 v98, 0xffff0000, v70
	v_lshlrev_b32_e32 v83, 16, v71
	v_and_b32_e32 v99, 0xffff0000, v71
	v_lshlrev_b32_e32 v84, 16, v72
	v_and_b32_e32 v100, 0xffff0000, v72
	v_lshlrev_b32_e32 v85, 16, v73
	v_and_b32_e32 v101, 0xffff0000, v73
	v_lshlrev_b32_e32 v86, 16, v74
	v_and_b32_e32 v102, 0xffff0000, v74
	v_lshlrev_b32_e32 v87, 16, v75
	v_and_b32_e32 v103, 0xffff0000, v75
	v_lshlrev_b32_e32 v88, 16, v76
	v_and_b32_e32 v89, 0xffff0000, v76
	v_lshlrev_b32_e32 v90, 16, v77
	v_and_b32_e32 v91, 0xffff0000, v77
	v_lshlrev_b32_e32 v92, 16, v78
	v_and_b32_e32 v93, 0xffff0000, v78
	v_lshlrev_b32_e32 v94, 16, v79
	v_and_b32_e32 v95, 0xffff0000, v79
	v_fmac_f32_e32 v80, v96, v18
	v_fmac_f32_e32 v81, v97, v19
	v_fmac_f32_e32 v82, v98, v20
	v_fmac_f32_e32 v83, v99, v21
	v_fmac_f32_e32 v84, v100, v22
	v_fmac_f32_e32 v85, v101, v23
	v_fmac_f32_e32 v86, v102, v24
	v_fmac_f32_e32 v87, v103, v25
	v_mul_f32_e32 v104, 0x3d372713, v88
	v_mul_f32_e32 v105, 0x3d372713, v89
	v_mul_f32_e32 v106, 0x3d372713, v90
	v_mul_f32_e32 v107, 0x3d372713, v91
	v_mul_f32_e32 v108, 0x3d372713, v92
	v_mul_f32_e32 v109, 0x3d372713, v93
	v_mul_f32_e32 v110, 0x3d372713, v94
	v_mul_f32_e32 v111, 0x3d372713, v95
	v_mul_f32_e32 v104, v104, v88
	v_mul_f32_e32 v105, v105, v89
	v_mul_f32_e32 v106, v106, v90
	v_mul_f32_e32 v107, v107, v91
; __device__ __forceinline__ u32x4 pack8(const float (&f)[8]) { u32x4 o; o.x = cvt_pk_bf16(f[0], f[1]); o.y = cvt_pk_bf16(f[2], f[3]); o.z = cvt_pk_bf16(f[4], f[5]); o.w = cvt_pk_bf16(f[6], f[7]); return o; }
; __device__ __forceinline__ float sigmoidf_(float x) { return __builtin_amdgcn_rcpf(1.0f + __expf(-x)); }
; __device__ __forceinline__ float gelu_tanh(float x) { return x * sigmoidf_(1.5957691216057308f * (x + 0.044715f * x * x * x)); }
; __device__ __forceinline__ void fixup_phase(KP p, int l) {
;     ...
;         for (int i = 0; i < 16; ++i) {
;             const size_t m = (size_t)(m0 + i);
;             float hl[8], pc[8], gr[8], o[8], h[8];
;             unpack8(__builtin_nontemporal_load((const u32x4*)(HLOC + m * D + c0)), hl); unpack8(__builtin_nontemporal_load((const u32x4*)(PCUM + m * D + c0)), pc);
;             bf16_t* gp = P + m * DP + C_GR + c0; unpack8(*(const u32x4*)gp, gr);
; #pragma unroll
;             for (int e = 0; e < 8; ++e) { h[e] = hl[e] + pc[e] * carry[e]; o[e] = gelu_tanh(gr[e]) * h[e]; }
;             *(u32x4*)gp = pack8(o);
	v_mul_f32_e32 v108, v108, v92
	v_mul_f32_e32 v109, v109, v93
	v_mul_f32_e32 v110, v110, v94
	v_mul_f32_e32 v111, v111, v95
	v_fma_f32 v104, v104, v88, v88
	v_fma_f32 v105, v105, v89, v89
	v_fma_f32 v106, v106, v90, v90
	v_fma_f32 v107, v107, v91, v91
	v_fma_f32 v108, v108, v92, v92
	v_fma_f32 v109, v109, v93, v93
	v_fma_f32 v110, v110, v94, v94
	v_fma_f32 v111, v111, v95, v95
	v_mul_f32_e32 v104, 0x3fcc422a, v104
	v_mul_f32_e32 v105, 0x3fcc422a, v105
	v_mul_f32_e32 v106, 0x3fcc422a, v106
	v_mul_f32_e32 v107, 0x3fcc422a, v107
	v_mul_f32_e32 v108, 0x3fcc422a, v108
	v_mul_f32_e32 v109, 0x3fcc422a, v109
	v_mul_f32_e32 v110, 0x3fcc422a, v110
	v_mul_f32_e32 v111, 0x3fcc422a, v111
	v_mul_f32_e32 v104, 0xbfb8aa3b, v104
	v_mul_f32_e32 v105, 0xbfb8aa3b, v105
	v_mul_f32_e32 v106, 0xbfb8aa3b, v106
	v_mul_f32_e32 v107, 0xbfb8aa3b, v107
	v_mul_f32_e32 v108, 0xbfb8aa3b, v108
	v_mul_f32_e32 v109, 0xbfb8aa3b, v109
	v_mul_f32_e32 v110, 0xbfb8aa3b, v110
	v_mul_f32_e32 v111, 0xbfb8aa3b, v111
	v_exp_f32_e32 v104, v104
	v_exp_f32_e32 v105, v105
	v_exp_f32_e32 v106, v106
	v_exp_f32_e32 v107, v107
	v_exp_f32_e32 v108, v108
	v_exp_f32_e32 v109, v109
	v_exp_f32_e32 v110, v110
	v_exp_f32_e32 v111, v111
	v_add_f32_e32 v104, 1.0, v104
	v_add_f32_e32 v105, 1.0, v105
	v_add_f32_e32 v106, 1.0, v106
	v_add_f32_e32 v107, 1.0, v107
	v_add_f32_e32 v108, 1.0, v108
	v_add_f32_e32 v109, 1.0, v109
	v_add_f32_e32 v110, 1.0, v110
	v_add_f32_e32 v111, 1.0, v111
	v_rcp_f32_e32 v104, v104
	v_rcp_f32_e32 v105, v105
	v_rcp_f32_e32 v106, v106
	v_rcp_f32_e32 v107, v107
	v_rcp_f32_e32 v108, v108
	v_rcp_f32_e32 v109, v109
	v_rcp_f32_e32 v110, v110
	v_rcp_f32_e32 v111, v111
	v_mul_f32_e32 v104, v104, v88
	v_mul_f32_e32 v105, v105, v89
	v_mul_f32_e32 v106, v106, v90
	v_mul_f32_e32 v107, v107, v91
	v_mul_f32_e32 v108, v108, v92
	v_mul_f32_e32 v109, v109, v93
	v_mul_f32_e32 v110, v110, v94
	v_mul_f32_e32 v111, v111, v95
	v_mul_f32_e32 v104, v80, v104
	v_mul_f32_e32 v105, v81, v105
	v_mul_f32_e32 v106, v82, v106
	v_mul_f32_e32 v107, v83, v107
	v_mul_f32_e32 v108, v84, v108
	v_mul_f32_e32 v109, v85, v109
	v_mul_f32_e32 v110, v86, v110
	v_mul_f32_e32 v111, v87, v111
	v_cvt_pk_bf16_f32 v112, v104, v105
	v_cvt_pk_bf16_f32 v113, v106, v107
	v_cvt_pk_bf16_f32 v114, v108, v109
	v_cvt_pk_bf16_f32 v115, v110, v111
	global_store_dwordx4 v27, v[112:115], s[24:25]
	s_add_u32 s24, s24, 0x2800
	s_addc_u32 s25, s25, 0
	global_load_dwordx4 v[68:71], v31, s[12:13]
	global_load_dwordx4 v[72:75], v31, s[12:13] offset:16
	global_load_dwordx4 v[76:79], v26, s[96:97] nt
	s_add_u32 s12, s12, 0x1000
	s_addc_u32 s13, s13, 0
	s_add_u32 s96, s96, 0x2800
	s_addc_u32 s97, s97, 0
	s_waitcnt vmcnt(12)
	v_lshlrev_b32_e32 v80, 16, v32
	v_and_b32_e32 v96, 0xffff0000, v32
	v_lshlrev_b32_e32 v81, 16, v33
	v_and_b32_e32 v97, 0xffff0000, v33
	v_lshlrev_b32_e32 v82, 16, v34
	v_and_b32_e32 v98, 0xffff0000, v34
	v_lshlrev_b32_e32 v83, 16, v35
	v_and_b32_e32 v99, 0xffff0000, v35
	v_lshlrev_b32_e32 v84, 16, v36
	v_and_b32_e32 v100, 0xffff0000, v36
	v_lshlrev_b32_e32 v85, 16, v37
	v_and_b32_e32 v101, 0xffff0000, v37
	v_lshlrev_b32_e32 v86, 16, v38
	v_and_b32_e32 v102, 0xffff0000, v38
	v_lshlrev_b32_e32 v87, 16, v39
	v_and_b32_e32 v103, 0xffff0000, v39
	v_lshlrev_b32_e32 v88, 16, v40
	v_and_b32_e32 v89, 0xffff0000, v40
	v_lshlrev_b32_e32 v90, 16, v41
	v_and_b32_e32 v91, 0xffff0000, v41
	v_lshlrev_b32_e32 v92, 16, v42
	v_and_b32_e32 v93, 0xffff0000, v42
	v_lshlrev_b32_e32 v94, 16, v43
	v_and_b32_e32 v95, 0xffff0000, v43
	v_fmac_f32_e32 v80, v96, v18
	v_fmac_f32_e32 v81, v97, v19
	v_fmac_f32_e32 v82, v98, v20
	v_fmac_f32_e32 v83, v99, v21
	v_fmac_f32_e32 v84, v100, v22
	v_fmac_f32_e32 v85, v101, v23
	v_fmac_f32_e32 v86, v102, v24
	v_fmac_f32_e32 v87, v103, v25
	v_mul_f32_e32 v104, 0x3d372713, v88
	v_mul_f32_e32 v105, 0x3d372713, v89
	v_mul_f32_e32 v106, 0x3d372713, v90
	v_mul_f32_e32 v107, 0x3d372713, v91
	v_mul_f32_e32 v108, 0x3d372713, v92
	v_mul_f32_e32 v109, 0x3d372713, v93
	v_mul_f32_e32 v110, 0x3d372713, v94
	v_mul_f32_e32 v111, 0x3d372713, v95
	v_mul_f32_e32 v104, v104, v88
	v_mul_f32_e32 v105, v105, v89
	v_mul_f32_e32 v106, v106, v90
	v_mul_f32_e32 v107, v107, v91
	v_mul_f32_e32 v108, v108, v92
	v_mul_f32_e32 v109, v109, v93
	v_mul_f32_e32 v110, v110, v94
	v_mul_f32_e32 v111, v111, v95
	v_fma_f32 v104, v104, v88, v88
	v_fma_f32 v105, v105, v89, v89
	v_fma_f32 v106, v106, v90, v90
	v_fma_f32 v107, v107, v91, v91
	v_fma_f32 v108, v108, v92, v92
	v_fma_f32 v109, v109, v93, v93
	v_fma_f32 v110, v110, v94, v94
	v_fma_f32 v111, v111, v95, v95
	v_mul_f32_e32 v104, 0x3fcc422a, v104
	v_mul_f32_e32 v105, 0x3fcc422a, v105
	v_mul_f32_e32 v106, 0x3fcc422a, v106
	v_mul_f32_e32 v107, 0x3fcc422a, v107
	v_mul_f32_e32 v108, 0x3fcc422a, v108
	v_mul_f32_e32 v109, 0x3fcc422a, v109
	v_mul_f32_e32 v110, 0x3fcc422a, v110
	v_mul_f32_e32 v111, 0x3fcc422a, v111
	v_mul_f32_e32 v104, 0xbfb8aa3b, v104
	v_mul_f32_e32 v105, 0xbfb8aa3b, v105
	v_mul_f32_e32 v106, 0xbfb8aa3b, v106
	v_mul_f32_e32 v107, 0xbfb8aa3b, v107
	v_mul_f32_e32 v108, 0xbfb8aa3b, v108
	v_mul_f32_e32 v109, 0xbfb8aa3b, v109
	v_mul_f32_e32 v110, 0xbfb8aa3b, v110
	v_mul_f32_e32 v111, 0xbfb8aa3b, v111
	v_exp_f32_e32 v104, v104
	v_exp_f32_e32 v105, v105
	v_exp_f32_e32 v106, v106
	v_exp_f32_e32 v107, v107
	v_exp_f32_e32 v108, v108
	v_exp_f32_e32 v109, v109
	v_exp_f32_e32 v110, v110
	v_exp_f32_e32 v111, v111
	v_add_f32_e32 v104, 1.0, v104
	v_add_f32_e32 v105, 1.0, v105
	v_add_f32_e32 v106, 1.0, v106
	v_add_f32_e32 v107, 1.0, v107
	v_add_f32_e32 v108, 1.0, v108
	v_add_f32_e32 v109, 1.0, v109
	v_add_f32_e32 v110, 1.0, v110
	v_add_f32_e32 v111, 1.0, v111
	v_rcp_f32_e32 v104, v104
	v_rcp_f32_e32 v105, v105
	v_rcp_f32_e32 v106, v106
	v_rcp_f32_e32 v107, v107
	v_rcp_f32_e32 v108, v108
	v_rcp_f32_e32 v109, v109
	v_rcp_f32_e32 v110, v110
	v_rcp_f32_e32 v111, v111
	v_mul_f32_e32 v104, v104, v88
	v_mul_f32_e32 v105, v105, v89
	v_mul_f32_e32 v106, v106, v90
	v_mul_f32_e32 v107, v107, v91
	v_mul_f32_e32 v108, v108, v92
	v_mul_f32_e32 v109, v109, v93
	v_mul_f32_e32 v110, v110, v94
	v_mul_f32_e32 v111, v111, v95
	v_mul_f32_e32 v104, v80, v104
	v_mul_f32_e32 v105, v81, v105
	v_mul_f32_e32 v106, v82, v106
	v_mul_f32_e32 v107, v83, v107
	v_mul_f32_e32 v108, v84, v108
	v_mul_f32_e32 v109, v85, v109
	v_mul_f32_e32 v110, v86, v110
	v_mul_f32_e32 v111, v87, v111
	v_cvt_pk_bf16_f32 v112, v104, v105
	v_cvt_pk_bf16_f32 v113, v106, v107
	v_cvt_pk_bf16_f32 v114, v108, v109
	v_cvt_pk_bf16_f32 v115, v110, v111
	global_store_dwordx4 v27, v[112:115], s[24:25]
	s_add_u32 s24, s24, 0x2800
	s_addc_u32 s25, s25, 0
	global_load_dwordx4 v[32:35], v31, s[12:13]
	global_load_dwordx4 v[36:39], v31, s[12:13] offset:16
	global_load_dwordx4 v[40:43], v26, s[96:97] nt
	s_add_u32 s12, s12, 0x1000
	s_addc_u32 s13, s13, 0
	s_add_u32 s96, s96, 0x2800
	s_addc_u32 s97, s97, 0
	s_waitcnt vmcnt(12)
; __device__ __forceinline__ u32x4 pack8(const float (&f)[8]) { u32x4 o; o.x = cvt_pk_bf16(f[0], f[1]); o.y = cvt_pk_bf16(f[2], f[3]); o.z = cvt_pk_bf16(f[4], f[5]); o.w = cvt_pk_bf16(f[6], f[7]); return o; }
; __device__ __forceinline__ float sigmoidf_(float x) { return __builtin_amdgcn_rcpf(1.0f + __expf(-x)); }
; __device__ __forceinline__ float gelu_tanh(float x) { return x * sigmoidf_(1.5957691216057308f * (x + 0.044715f * x * x * x)); }
; __device__ __forceinline__ void fixup_phase(KP p, int l) {
;     ...
;         for (int i = 0; i < 16; ++i) {
;             const size_t m = (size_t)(m0 + i);
;             float hl[8], pc[8], gr[8], o[8], h[8];
;             unpack8(__builtin_nontemporal_load((const u32x4*)(HLOC + m * D + c0)), hl); unpack8(__builtin_nontemporal_load((const u32x4*)(PCUM + m * D + c0)), pc);
;             bf16_t* gp = P + m * DP + C_GR + c0; unpack8(*(const u32x4*)gp, gr);
; #pragma unroll
;             for (int e = 0; e < 8; ++e) { h[e] = hl[e] + pc[e] * carry[e]; o[e] = gelu_tanh(gr[e]) * h[e]; }
;             *(u32x4*)gp = pack8(o);
	v_lshlrev_b32_e32 v80, 16, v44
	v_and_b32_e32 v96, 0xffff0000, v44
	v_lshlrev_b32_e32 v81, 16, v45
	v_and_b32_e32 v97, 0xffff0000, v45
	v_lshlrev_b32_e32 v82, 16, v46
	v_and_b32_e32 v98, 0xffff0000, v46
	v_lshlrev_b32_e32 v83, 16, v47
	v_and_b32_e32 v99, 0xffff0000, v47
	v_lshlrev_b32_e32 v84, 16, v48
	v_and_b32_e32 v100, 0xffff0000, v48
	v_lshlrev_b32_e32 v85, 16, v49
	v_and_b32_e32 v101, 0xffff0000, v49
	v_lshlrev_b32_e32 v86, 16, v50
	v_and_b32_e32 v102, 0xffff0000, v50
	v_lshlrev_b32_e32 v87, 16, v51
	v_and_b32_e32 v103, 0xffff0000, v51
	v_lshlrev_b32_e32 v88, 16, v52
	v_and_b32_e32 v89, 0xffff0000, v52
	v_lshlrev_b32_e32 v90, 16, v53
	v_and_b32_e32 v91, 0xffff0000, v53
	v_lshlrev_b32_e32 v92, 16, v54
	v_and_b32_e32 v93, 0xffff0000, v54
	v_lshlrev_b32_e32 v94, 16, v55
	v_and_b32_e32 v95, 0xffff0000, v55
	v_fmac_f32_e32 v80, v96, v18
	v_fmac_f32_e32 v81, v97, v19
	v_fmac_f32_e32 v82, v98, v20
	v_fmac_f32_e32 v83, v99, v21
	v_fmac_f32_e32 v84, v100, v22
	v_fmac_f32_e32 v85, v101, v23
	v_fmac_f32_e32 v86, v102, v24
	v_fmac_f32_e32 v87, v103, v25
	v_mul_f32_e32 v104, 0x3d372713, v88
	v_mul_f32_e32 v105, 0x3d372713, v89
	v_mul_f32_e32 v106, 0x3d372713, v90
	v_mul_f32_e32 v107, 0x3d372713, v91
	v_mul_f32_e32 v108, 0x3d372713, v92
	v_mul_f32_e32 v109, 0x3d372713, v93
	v_mul_f32_e32 v110, 0x3d372713, v94
	v_mul_f32_e32 v111, 0x3d372713, v95
	v_mul_f32_e32 v104, v104, v88
	v_mul_f32_e32 v105, v105, v89
	v_mul_f32_e32 v106, v106, v90
	v_mul_f32_e32 v107, v107, v91
	v_mul_f32_e32 v108, v108, v92
	v_mul_f32_e32 v109, v109, v93
	v_mul_f32_e32 v110, v110, v94
	v_mul_f32_e32 v111, v111, v95
	v_fma_f32 v104, v104, v88, v88
	v_fma_f32 v105, v105, v89, v89
	v_fma_f32 v106, v106, v90, v90
	v_fma_f32 v107, v107, v91, v91
	v_fma_f32 v108, v108, v92, v92
	v_fma_f32 v109, v109, v93, v93
	v_fma_f32 v110, v110, v94, v94
	v_fma_f32 v111, v111, v95, v95
	v_mul_f32_e32 v104, 0x3fcc422a, v104
	v_mul_f32_e32 v105, 0x3fcc422a, v105
	v_mul_f32_e32 v106, 0x3fcc422a, v106
	v_mul_f32_e32 v107, 0x3fcc422a, v107
	v_mul_f32_e32 v108, 0x3fcc422a, v108
	v_mul_f32_e32 v109, 0x3fcc422a, v109
	v_mul_f32_e32 v110, 0x3fcc422a, v110
	v_mul_f32_e32 v111, 0x3fcc422a, v111
	v_mul_f32_e32 v104, 0xbfb8aa3b, v104
	v_mul_f32_e32 v105, 0xbfb8aa3b, v105
	v_mul_f32_e32 v106, 0xbfb8aa3b, v106
	v_mul_f32_e32 v107, 0xbfb8aa3b, v107
	v_mul_f32_e32 v108, 0xbfb8aa3b, v108
	v_mul_f32_e32 v109, 0xbfb8aa3b, v109
	v_mul_f32_e32 v110, 0xbfb8aa3b, v110
	v_mul_f32_e32 v111, 0xbfb8aa3b, v111
	v_exp_f32_e32 v104, v104
	v_exp_f32_e32 v105, v105
	v_exp_f32_e32 v106, v106
	v_exp_f32_e32 v107, v107
	v_exp_f32_e32 v108, v108
	v_exp_f32_e32 v109, v109
	v_exp_f32_e32 v110, v110
	v_exp_f32_e32 v111, v111
	v_add_f32_e32 v104, 1.0, v104
	v_add_f32_e32 v105, 1.0, v105
	v_add_f32_e32 v106, 1.0, v106
	v_add_f32_e32 v107, 1.0, v107
	v_add_f32_e32 v108, 1.0, v108
	v_add_f32_e32 v109, 1.0, v109
	v_add_f32_e32 v110, 1.0, v110
	v_add_f32_e32 v111, 1.0, v111
	v_rcp_f32_e32 v104, v104
	v_rcp_f32_e32 v105, v105
	v_rcp_f32_e32 v106, v106
	v_rcp_f32_e32 v107, v107
	v_rcp_f32_e32 v108, v108
	v_rcp_f32_e32 v109, v109
	v_rcp_f32_e32 v110, v110
	v_rcp_f32_e32 v111, v111
	v_mul_f32_e32 v104, v104, v88
	v_mul_f32_e32 v105, v105, v89
	v_mul_f32_e32 v106, v106, v90
	v_mul_f32_e32 v107, v107, v91
	v_mul_f32_e32 v108, v108, v92
	v_mul_f32_e32 v109, v109, v93
	v_mul_f32_e32 v110, v110, v94
	v_mul_f32_e32 v111, v111, v95
	v_mul_f32_e32 v104, v80, v104
	v_mul_f32_e32 v105, v81, v105
	v_mul_f32_e32 v106, v82, v106
	v_mul_f32_e32 v107, v83, v107
	v_mul_f32_e32 v108, v84, v108
	v_mul_f32_e32 v109, v85, v109
	v_mul_f32_e32 v110, v86, v110
	v_mul_f32_e32 v111, v87, v111
	v_cvt_pk_bf16_f32 v112, v104, v105
	v_cvt_pk_bf16_f32 v113, v106, v107
	v_cvt_pk_bf16_f32 v114, v108, v109
	v_cvt_pk_bf16_f32 v115, v110, v111
	global_store_dwordx4 v27, v[112:115], s[24:25]
	s_add_u32 s24, s24, 0x2800
	s_addc_u32 s25, s25, 0
	global_load_dwordx4 v[44:47], v31, s[12:13]
	global_load_dwordx4 v[48:51], v31, s[12:13] offset:16
	global_load_dwordx4 v[52:55], v26, s[96:97] nt
	s_add_u32 s12, s12, 0x1000
	s_addc_u32 s13, s13, 0
	s_add_u32 s96, s96, 0x2800
	s_addc_u32 s97, s97, 0
	s_waitcnt vmcnt(12)
	v_lshlrev_b32_e32 v80, 16, v56
	v_and_b32_e32 v96, 0xffff0000, v56
	v_lshlrev_b32_e32 v81, 16, v57
	v_and_b32_e32 v97, 0xffff0000, v57
	v_lshlrev_b32_e32 v82, 16, v58
	v_and_b32_e32 v98, 0xffff0000, v58
	v_lshlrev_b32_e32 v83, 16, v59
	v_and_b32_e32 v99, 0xffff0000, v59
	v_lshlrev_b32_e32 v84, 16, v60
	v_and_b32_e32 v100, 0xffff0000, v60
	v_lshlrev_b32_e32 v85, 16, v61
	v_and_b32_e32 v101, 0xffff0000, v61
	v_lshlrev_b32_e32 v86, 16, v62
	v_and_b32_e32 v102, 0xffff0000, v62
	v_lshlrev_b32_e32 v87, 16, v63
	v_and_b32_e32 v103, 0xffff0000, v63
	v_lshlrev_b32_e32 v88, 16, v64
	v_and_b32_e32 v89, 0xffff0000, v64
	v_lshlrev_b32_e32 v90, 16, v65
	v_and_b32_e32 v91, 0xffff0000, v65
	v_lshlrev_b32_e32 v92, 16, v66
	v_and_b32_e32 v93, 0xffff0000, v66
	v_lshlrev_b32_e32 v94, 16, v67
	v_and_b32_e32 v95, 0xffff0000, v67
	v_fmac_f32_e32 v80, v96, v18
	v_fmac_f32_e32 v81, v97, v19
	v_fmac_f32_e32 v82, v98, v20
	v_fmac_f32_e32 v83, v99, v21
	v_fmac_f32_e32 v84, v100, v22
	v_fmac_f32_e32 v85, v101, v23
	v_fmac_f32_e32 v86, v102, v24
	v_fmac_f32_e32 v87, v103, v25
	v_mul_f32_e32 v104, 0x3d372713, v88
	v_mul_f32_e32 v105, 0x3d372713, v89
	v_mul_f32_e32 v106, 0x3d372713, v90
	v_mul_f32_e32 v107, 0x3d372713, v91
	v_mul_f32_e32 v108, 0x3d372713, v92
	v_mul_f32_e32 v109, 0x3d372713, v93
	v_mul_f32_e32 v110, 0x3d372713, v94
	v_mul_f32_e32 v111, 0x3d372713, v95
	v_mul_f32_e32 v104, v104, v88
	v_mul_f32_e32 v105, v105, v89
	v_mul_f32_e32 v106, v106, v90
	v_mul_f32_e32 v107, v107, v91
; __device__ __forceinline__ u32x4 pack8(const float (&f)[8]) { u32x4 o; o.x = cvt_pk_bf16(f[0], f[1]); o.y = cvt_pk_bf16(f[2], f[3]); o.z = cvt_pk_bf16(f[4], f[5]); o.w = cvt_pk_bf16(f[6], f[7]); return o; }
; __device__ __forceinline__ float sigmoidf_(float x) { return __builtin_amdgcn_rcpf(1.0f + __expf(-x)); }
; __device__ __forceinline__ float gelu_tanh(float x) { return x * sigmoidf_(1.5957691216057308f * (x + 0.044715f * x * x * x)); }
; __device__ __forceinline__ void fixup_phase(KP p, int l) {
;     ...
;         for (int i = 0; i < 16; ++i) {
;             const size_t m = (size_t)(m0 + i);
;             float hl[8], pc[8], gr[8], o[8], h[8];
;             unpack8(__builtin_nontemporal_load((const u32x4*)(HLOC + m * D + c0)), hl); unpack8(__builtin_nontemporal_load((const u32x4*)(PCUM + m * D + c0)), pc);
;             bf16_t* gp = P + m * DP + C_GR + c0; unpack8(*(const u32x4*)gp, gr);
; #pragma unroll
;             for (int e = 0; e < 8; ++e) { h[e] = hl[e] + pc[e] * carry[e]; o[e] = gelu_tanh(gr[e]) * h[e]; }
;             *(u32x4*)gp = pack8(o);
	v_mul_f32_e32 v108, v108, v92
	v_mul_f32_e32 v109, v109, v93
	v_mul_f32_e32 v110, v110, v94
	v_mul_f32_e32 v111, v111, v95
	v_fma_f32 v104, v104, v88, v88
	v_fma_f32 v105, v105, v89, v89
	v_fma_f32 v106, v106, v90, v90
	v_fma_f32 v107, v107, v91, v91
	v_fma_f32 v108, v108, v92, v92
	v_fma_f32 v109, v109, v93, v93
	v_fma_f32 v110, v110, v94, v94
	v_fma_f32 v111, v111, v95, v95
	v_mul_f32_e32 v104, 0x3fcc422a, v104
	v_mul_f32_e32 v105, 0x3fcc422a, v105
	v_mul_f32_e32 v106, 0x3fcc422a, v106
	v_mul_f32_e32 v107, 0x3fcc422a, v107
	v_mul_f32_e32 v108, 0x3fcc422a, v108
	v_mul_f32_e32 v109, 0x3fcc422a, v109
	v_mul_f32_e32 v110, 0x3fcc422a, v110
	v_mul_f32_e32 v111, 0x3fcc422a, v111
	v_mul_f32_e32 v104, 0xbfb8aa3b, v104
	v_mul_f32_e32 v105, 0xbfb8aa3b, v105
	v_mul_f32_e32 v106, 0xbfb8aa3b, v106
	v_mul_f32_e32 v107, 0xbfb8aa3b, v107
	v_mul_f32_e32 v108, 0xbfb8aa3b, v108
	v_mul_f32_e32 v109, 0xbfb8aa3b, v109
	v_mul_f32_e32 v110, 0xbfb8aa3b, v110
	v_mul_f32_e32 v111, 0xbfb8aa3b, v111
	v_exp_f32_e32 v104, v104
	v_exp_f32_e32 v105, v105
	v_exp_f32_e32 v106, v106
	v_exp_f32_e32 v107, v107
	v_exp_f32_e32 v108, v108
	v_exp_f32_e32 v109, v109
	v_exp_f32_e32 v110, v110
	v_exp_f32_e32 v111, v111
	v_add_f32_e32 v104, 1.0, v104
	v_add_f32_e32 v105, 1.0, v105
	v_add_f32_e32 v106, 1.0, v106
	v_add_f32_e32 v107, 1.0, v107
	v_add_f32_e32 v108, 1.0, v108
	v_add_f32_e32 v109, 1.0, v109
	v_add_f32_e32 v110, 1.0, v110
	v_add_f32_e32 v111, 1.0, v111
	v_rcp_f32_e32 v104, v104
	v_rcp_f32_e32 v105, v105
	v_rcp_f32_e32 v106, v106
	v_rcp_f32_e32 v107, v107
	v_rcp_f32_e32 v108, v108
	v_rcp_f32_e32 v109, v109
	v_rcp_f32_e32 v110, v110
	v_rcp_f32_e32 v111, v111
	v_mul_f32_e32 v104, v104, v88
	v_mul_f32_e32 v105, v105, v89
	v_mul_f32_e32 v106, v106, v90
	v_mul_f32_e32 v107, v107, v91
	v_mul_f32_e32 v108, v108, v92
	v_mul_f32_e32 v109, v109, v93
	v_mul_f32_e32 v110, v110, v94
	v_mul_f32_e32 v111, v111, v95
	v_mul_f32_e32 v104, v80, v104
	v_mul_f32_e32 v105, v81, v105
	v_mul_f32_e32 v106, v82, v106
	v_mul_f32_e32 v107, v83, v107
	v_mul_f32_e32 v108, v84, v108
	v_mul_f32_e32 v109, v85, v109
	v_mul_f32_e32 v110, v86, v110
	v_mul_f32_e32 v111, v87, v111
	v_cvt_pk_bf16_f32 v112, v104, v105
	v_cvt_pk_bf16_f32 v113, v106, v107
	v_cvt_pk_bf16_f32 v114, v108, v109
	v_cvt_pk_bf16_f32 v115, v110, v111
	global_store_dwordx4 v27, v[112:115], s[24:25]
	s_add_u32 s24, s24, 0x2800
	s_addc_u32 s25, s25, 0
	global_load_dwordx4 v[56:59], v31, s[12:13]
	global_load_dwordx4 v[60:63], v31, s[12:13] offset:16
	global_load_dwordx4 v[64:67], v26, s[96:97] nt
	s_add_u32 s12, s12, 0x1000
	s_addc_u32 s13, s13, 0
	s_add_u32 s96, s96, 0x2800
	s_addc_u32 s97, s97, 0
	s_waitcnt vmcnt(12)
	v_lshlrev_b32_e32 v80, 16, v68
	v_and_b32_e32 v96, 0xffff0000, v68
	v_lshlrev_b32_e32 v81, 16, v69
	v_and_b32_e32 v97, 0xffff0000, v69
	v_lshlrev_b32_e32 v82, 16, v70
	v_and_b32_e32 v98, 0xffff0000, v70
	v_lshlrev_b32_e32 v83, 16, v71
	v_and_b32_e32 v99, 0xffff0000, v71
	v_lshlrev_b32_e32 v84, 16, v72
	v_and_b32_e32 v100, 0xffff0000, v72
	v_lshlrev_b32_e32 v85, 16, v73
	v_and_b32_e32 v101, 0xffff0000, v73
	v_lshlrev_b32_e32 v86, 16, v74
	v_and_b32_e32 v102, 0xffff0000, v74
	v_lshlrev_b32_e32 v87, 16, v75
	v_and_b32_e32 v103, 0xffff0000, v75
	v_lshlrev_b32_e32 v88, 16, v76
	v_and_b32_e32 v89, 0xffff0000, v76
	v_lshlrev_b32_e32 v90, 16, v77
	v_and_b32_e32 v91, 0xffff0000, v77
	v_lshlrev_b32_e32 v92, 16, v78
	v_and_b32_e32 v93, 0xffff0000, v78
	v_lshlrev_b32_e32 v94, 16, v79
	v_and_b32_e32 v95, 0xffff0000, v79
	v_fmac_f32_e32 v80, v96, v18
	v_fmac_f32_e32 v81, v97, v19
	v_fmac_f32_e32 v82, v98, v20
	v_fmac_f32_e32 v83, v99, v21
	v_fmac_f32_e32 v84, v100, v22
	v_fmac_f32_e32 v85, v101, v23
	v_fmac_f32_e32 v86, v102, v24
	v_fmac_f32_e32 v87, v103, v25
	v_mul_f32_e32 v104, 0x3d372713, v88
	v_mul_f32_e32 v105, 0x3d372713, v89
	v_mul_f32_e32 v106, 0x3d372713, v90
	v_mul_f32_e32 v107, 0x3d372713, v91
	v_mul_f32_e32 v108, 0x3d372713, v92
	v_mul_f32_e32 v109, 0x3d372713, v93
	v_mul_f32_e32 v110, 0x3d372713, v94
	v_mul_f32_e32 v111, 0x3d372713, v95
	v_mul_f32_e32 v104, v104, v88
	v_mul_f32_e32 v105, v105, v89
	v_mul_f32_e32 v106, v106, v90
	v_mul_f32_e32 v107, v107, v91
	v_mul_f32_e32 v108, v108, v92
	v_mul_f32_e32 v109, v109, v93
	v_mul_f32_e32 v110, v110, v94
	v_mul_f32_e32 v111, v111, v95
	v_fma_f32 v104, v104, v88, v88
	v_fma_f32 v105, v105, v89, v89
	v_fma_f32 v106, v106, v90, v90
	v_fma_f32 v107, v107, v91, v91
	v_fma_f32 v108, v108, v92, v92
	v_fma_f32 v109, v109, v93, v93
	v_fma_f32 v110, v110, v94, v94
	v_fma_f32 v111, v111, v95, v95
	v_mul_f32_e32 v104, 0x3fcc422a, v104
	v_mul_f32_e32 v105, 0x3fcc422a, v105
	v_mul_f32_e32 v106, 0x3fcc422a, v106
	v_mul_f32_e32 v107, 0x3fcc422a, v107
	v_mul_f32_e32 v108, 0x3fcc422a, v108
	v_mul_f32_e32 v109, 0x3fcc422a, v109
	v_mul_f32_e32 v110, 0x3fcc422a, v110
	v_mul_f32_e32 v111, 0x3fcc422a, v111
	v_mul_f32_e32 v104, 0xbfb8aa3b, v104
	v_mul_f32_e32 v105, 0xbfb8aa3b, v105
	v_mul_f32_e32 v106, 0xbfb8aa3b, v106
	v_mul_f32_e32 v107, 0xbfb8aa3b, v107
	v_mul_f32_e32 v108, 0xbfb8aa3b, v108
	v_mul_f32_e32 v109, 0xbfb8aa3b, v109
	v_mul_f32_e32 v110, 0xbfb8aa3b, v110
	v_mul_f32_e32 v111, 0xbfb8aa3b, v111
	v_exp_f32_e32 v104, v104
	v_exp_f32_e32 v105, v105
	v_exp_f32_e32 v106, v106
	v_exp_f32_e32 v107, v107
	v_exp_f32_e32 v108, v108
	v_exp_f32_e32 v109, v109
	v_exp_f32_e32 v110, v110
	v_exp_f32_e32 v111, v111
	v_add_f32_e32 v104, 1.0, v104
	v_add_f32_e32 v105, 1.0, v105
	v_add_f32_e32 v106, 1.0, v106
	v_add_f32_e32 v107, 1.0, v107
	v_add_f32_e32 v108, 1.0, v108
	v_add_f32_e32 v109, 1.0, v109
	v_add_f32_e32 v110, 1.0, v110
	v_add_f32_e32 v111, 1.0, v111
	v_rcp_f32_e32 v104, v104
	v_rcp_f32_e32 v105, v105
	v_rcp_f32_e32 v106, v106
	v_rcp_f32_e32 v107, v107
	v_rcp_f32_e32 v108, v108
	v_rcp_f32_e32 v109, v109
	v_rcp_f32_e32 v110, v110
	v_rcp_f32_e32 v111, v111
	v_mul_f32_e32 v104, v104, v88
	v_mul_f32_e32 v105, v105, v89
	v_mul_f32_e32 v106, v106, v90
	v_mul_f32_e32 v107, v107, v91
	v_mul_f32_e32 v108, v108, v92
	v_mul_f32_e32 v109, v109, v93
	v_mul_f32_e32 v110, v110, v94
	v_mul_f32_e32 v111, v111, v95
	v_mul_f32_e32 v104, v80, v104
	v_mul_f32_e32 v105, v81, v105
	v_mul_f32_e32 v106, v82, v106
	v_mul_f32_e32 v107, v83, v107
	v_mul_f32_e32 v108, v84, v108
	v_mul_f32_e32 v109, v85, v109
	v_mul_f32_e32 v110, v86, v110
	v_mul_f32_e32 v111, v87, v111
	v_cvt_pk_bf16_f32 v112, v104, v105
	v_cvt_pk_bf16_f32 v113, v106, v107
	v_cvt_pk_bf16_f32 v114, v108, v109
	v_cvt_pk_bf16_f32 v115, v110, v111
	global_store_dwordx4 v27, v[112:115], s[24:25]
	s_add_u32 s24, s24, 0x2800
	s_addc_u32 s25, s25, 0
	global_load_dwordx4 v[68:71], v31, s[12:13]
	global_load_dwordx4 v[72:75], v31, s[12:13] offset:16
	global_load_dwordx4 v[76:79], v26, s[96:97] nt
	s_add_u32 s12, s12, 0x1000
	s_addc_u32 s13, s13, 0
	s_add_u32 s96, s96, 0x2800
	s_addc_u32 s97, s97, 0
	s_waitcnt vmcnt(12)
; __device__ __forceinline__ u32x4 pack8(const float (&f)[8]) { u32x4 o; o.x = cvt_pk_bf16(f[0], f[1]); o.y = cvt_pk_bf16(f[2], f[3]); o.z = cvt_pk_bf16(f[4], f[5]); o.w = cvt_pk_bf16(f[6], f[7]); return o; }
; __device__ __forceinline__ float sigmoidf_(float x) { return __builtin_amdgcn_rcpf(1.0f + __expf(-x)); }
; __device__ __forceinline__ float gelu_tanh(float x) { return x * sigmoidf_(1.5957691216057308f * (x + 0.044715f * x * x * x)); }
; __device__ __forceinline__ void fixup_phase(KP p, int l) {
;     ...
;         for (int i = 0; i < 16; ++i) {
;             const size_t m = (size_t)(m0 + i);
;             float hl[8], pc[8], gr[8], o[8], h[8];
;             unpack8(__builtin_nontemporal_load((const u32x4*)(HLOC + m * D + c0)), hl); unpack8(__builtin_nontemporal_load((const u32x4*)(PCUM + m * D + c0)), pc);
;             bf16_t* gp = P + m * DP + C_GR + c0; unpack8(*(const u32x4*)gp, gr);
; #pragma unroll
;             for (int e = 0; e < 8; ++e) { h[e] = hl[e] + pc[e] * carry[e]; o[e] = gelu_tanh(gr[e]) * h[e]; }
;             *(u32x4*)gp = pack8(o);
	v_lshlrev_b32_e32 v80, 16, v32
	v_and_b32_e32 v96, 0xffff0000, v32
	v_lshlrev_b32_e32 v81, 16, v33
	v_and_b32_e32 v97, 0xffff0000, v33
	v_lshlrev_b32_e32 v82, 16, v34
	v_and_b32_e32 v98, 0xffff0000, v34
	v_lshlrev_b32_e32 v83, 16, v35
	v_and_b32_e32 v99, 0xffff0000, v35
	v_lshlrev_b32_e32 v84, 16, v36
	v_and_b32_e32 v100, 0xffff0000, v36
	v_lshlrev_b32_e32 v85, 16, v37
	v_and_b32_e32 v101, 0xffff0000, v37
	v_lshlrev_b32_e32 v86, 16, v38
	v_and_b32_e32 v102, 0xffff0000, v38
	v_lshlrev_b32_e32 v87, 16, v39
	v_and_b32_e32 v103, 0xffff0000, v39
	v_lshlrev_b32_e32 v88, 16, v40
	v_and_b32_e32 v89, 0xffff0000, v40
	v_lshlrev_b32_e32 v90, 16, v41
	v_and_b32_e32 v91, 0xffff0000, v41
	v_lshlrev_b32_e32 v92, 16, v42
	v_and_b32_e32 v93, 0xffff0000, v42
	v_lshlrev_b32_e32 v94, 16, v43
	v_and_b32_e32 v95, 0xffff0000, v43
	v_fmac_f32_e32 v80, v96, v18
	v_fmac_f32_e32 v81, v97, v19
	v_fmac_f32_e32 v82, v98, v20
	v_fmac_f32_e32 v83, v99, v21
	v_fmac_f32_e32 v84, v100, v22
	v_fmac_f32_e32 v85, v101, v23
	v_fmac_f32_e32 v86, v102, v24
	v_fmac_f32_e32 v87, v103, v25
	v_mul_f32_e32 v104, 0x3d372713, v88
	v_mul_f32_e32 v105, 0x3d372713, v89
	v_mul_f32_e32 v106, 0x3d372713, v90
	v_mul_f32_e32 v107, 0x3d372713, v91
	v_mul_f32_e32 v108, 0x3d372713, v92
	v_mul_f32_e32 v109, 0x3d372713, v93
	v_mul_f32_e32 v110, 0x3d372713, v94
	v_mul_f32_e32 v111, 0x3d372713, v95
	v_mul_f32_e32 v104, v104, v88
	v_mul_f32_e32 v105, v105, v89
	v_mul_f32_e32 v106, v106, v90
	v_mul_f32_e32 v107, v107, v91
	v_mul_f32_e32 v108, v108, v92
	v_mul_f32_e32 v109, v109, v93
	v_mul_f32_e32 v110, v110, v94
	v_mul_f32_e32 v111, v111, v95
	v_fma_f32 v104, v104, v88, v88
	v_fma_f32 v105, v105, v89, v89
	v_fma_f32 v106, v106, v90, v90
	v_fma_f32 v107, v107, v91, v91
	v_fma_f32 v108, v108, v92, v92
	v_fma_f32 v109, v109, v93, v93
	v_fma_f32 v110, v110, v94, v94
	v_fma_f32 v111, v111, v95, v95
	v_mul_f32_e32 v104, 0x3fcc422a, v104
	v_mul_f32_e32 v105, 0x3fcc422a, v105
	v_mul_f32_e32 v106, 0x3fcc422a, v106
	v_mul_f32_e32 v107, 0x3fcc422a, v107
	v_mul_f32_e32 v108, 0x3fcc422a, v108
	v_mul_f32_e32 v109, 0x3fcc422a, v109
	v_mul_f32_e32 v110, 0x3fcc422a, v110
	v_mul_f32_e32 v111, 0x3fcc422a, v111
	v_mul_f32_e32 v104, 0xbfb8aa3b, v104
	v_mul_f32_e32 v105, 0xbfb8aa3b, v105
	v_mul_f32_e32 v106, 0xbfb8aa3b, v106
	v_mul_f32_e32 v107, 0xbfb8aa3b, v107
	v_mul_f32_e32 v108, 0xbfb8aa3b, v108
	v_mul_f32_e32 v109, 0xbfb8aa3b, v109
	v_mul_f32_e32 v110, 0xbfb8aa3b, v110
	v_mul_f32_e32 v111, 0xbfb8aa3b, v111
	v_exp_f32_e32 v104, v104
	v_exp_f32_e32 v105, v105
	v_exp_f32_e32 v106, v106
	v_exp_f32_e32 v107, v107
	v_exp_f32_e32 v108, v108
	v_exp_f32_e32 v109, v109
	v_exp_f32_e32 v110, v110
	v_exp_f32_e32 v111, v111
	v_add_f32_e32 v104, 1.0, v104
	v_add_f32_e32 v105, 1.0, v105
	v_add_f32_e32 v106, 1.0, v106
	v_add_f32_e32 v107, 1.0, v107
	v_add_f32_e32 v108, 1.0, v108
	v_add_f32_e32 v109, 1.0, v109
	v_add_f32_e32 v110, 1.0, v110
	v_add_f32_e32 v111, 1.0, v111
	v_rcp_f32_e32 v104, v104
	v_rcp_f32_e32 v105, v105
	v_rcp_f32_e32 v106, v106
	v_rcp_f32_e32 v107, v107
	v_rcp_f32_e32 v108, v108
	v_rcp_f32_e32 v109, v109
	v_rcp_f32_e32 v110, v110
	v_rcp_f32_e32 v111, v111
	v_mul_f32_e32 v104, v104, v88
	v_mul_f32_e32 v105, v105, v89
	v_mul_f32_e32 v106, v106, v90
	v_mul_f32_e32 v107, v107, v91
	v_mul_f32_e32 v108, v108, v92
	v_mul_f32_e32 v109, v109, v93
	v_mul_f32_e32 v110, v110, v94
	v_mul_f32_e32 v111, v111, v95
	v_mul_f32_e32 v104, v80, v104
	v_mul_f32_e32 v105, v81, v105
	v_mul_f32_e32 v106, v82, v106
	v_mul_f32_e32 v107, v83, v107
	v_mul_f32_e32 v108, v84, v108
	v_mul_f32_e32 v109, v85, v109
	v_mul_f32_e32 v110, v86, v110
	v_mul_f32_e32 v111, v87, v111
	v_cvt_pk_bf16_f32 v112, v104, v105
	v_cvt_pk_bf16_f32 v113, v106, v107
	v_cvt_pk_bf16_f32 v114, v108, v109
	v_cvt_pk_bf16_f32 v115, v110, v111
	global_store_dwordx4 v27, v[112:115], s[24:25]
	s_add_u32 s24, s24, 0x2800
	s_addc_u32 s25, s25, 0
	s_waitcnt vmcnt(9)
	v_lshlrev_b32_e32 v80, 16, v44
	v_and_b32_e32 v96, 0xffff0000, v44
	v_lshlrev_b32_e32 v81, 16, v45
	v_and_b32_e32 v97, 0xffff0000, v45
	v_lshlrev_b32_e32 v82, 16, v46
	v_and_b32_e32 v98, 0xffff0000, v46
	v_lshlrev_b32_e32 v83, 16, v47
	v_and_b32_e32 v99, 0xffff0000, v47
	v_lshlrev_b32_e32 v84, 16, v48
	v_and_b32_e32 v100, 0xffff0000, v48
	v_lshlrev_b32_e32 v85, 16, v49
	v_and_b32_e32 v101, 0xffff0000, v49
	v_lshlrev_b32_e32 v86, 16, v50
	v_and_b32_e32 v102, 0xffff0000, v50
	v_lshlrev_b32_e32 v87, 16, v51
	v_and_b32_e32 v103, 0xffff0000, v51
	v_lshlrev_b32_e32 v88, 16, v52
	v_and_b32_e32 v89, 0xffff0000, v52
	v_lshlrev_b32_e32 v90, 16, v53
	v_and_b32_e32 v91, 0xffff0000, v53
	v_lshlrev_b32_e32 v92, 16, v54
	v_and_b32_e32 v93, 0xffff0000, v54
	v_lshlrev_b32_e32 v94, 16, v55
	v_and_b32_e32 v95, 0xffff0000, v55
	v_fmac_f32_e32 v80, v96, v18
	v_fmac_f32_e32 v81, v97, v19
	v_fmac_f32_e32 v82, v98, v20
	v_fmac_f32_e32 v83, v99, v21
	v_fmac_f32_e32 v84, v100, v22
	v_fmac_f32_e32 v85, v101, v23
	v_fmac_f32_e32 v86, v102, v24
	v_fmac_f32_e32 v87, v103, v25
	v_mul_f32_e32 v104, 0x3d372713, v88
	v_mul_f32_e32 v105, 0x3d372713, v89
	v_mul_f32_e32 v106, 0x3d372713, v90
	v_mul_f32_e32 v107, 0x3d372713, v91
	v_mul_f32_e32 v108, 0x3d372713, v92
	v_mul_f32_e32 v109, 0x3d372713, v93
	v_mul_f32_e32 v110, 0x3d372713, v94
	v_mul_f32_e32 v111, 0x3d372713, v95
	v_mul_f32_e32 v104, v104, v88
	v_mul_f32_e32 v105, v105, v89
	v_mul_f32_e32 v106, v106, v90
	v_mul_f32_e32 v107, v107, v91
	v_mul_f32_e32 v108, v108, v92
	v_mul_f32_e32 v109, v109, v93
	v_mul_f32_e32 v110, v110, v94
	v_mul_f32_e32 v111, v111, v95
	v_fma_f32 v104, v104, v88, v88
	v_fma_f32 v105, v105, v89, v89
	v_fma_f32 v106, v106, v90, v90
	v_fma_f32 v107, v107, v91, v91
; __device__ __forceinline__ u32x4 pack8(const float (&f)[8]) { u32x4 o; o.x = cvt_pk_bf16(f[0], f[1]); o.y = cvt_pk_bf16(f[2], f[3]); o.z = cvt_pk_bf16(f[4], f[5]); o.w = cvt_pk_bf16(f[6], f[7]); return o; }
; __device__ __forceinline__ float sigmoidf_(float x) { return __builtin_amdgcn_rcpf(1.0f + __expf(-x)); }
; __device__ __forceinline__ float gelu_tanh(float x) { return x * sigmoidf_(1.5957691216057308f * (x + 0.044715f * x * x * x)); }
; __device__ __forceinline__ void fixup_phase(KP p, int l) {
;     ...
;         for (int i = 0; i < 16; ++i) {
;             const size_t m = (size_t)(m0 + i);
;             float hl[8], pc[8], gr[8], o[8], h[8];
;             unpack8(__builtin_nontemporal_load((const u32x4*)(HLOC + m * D + c0)), hl); unpack8(__builtin_nontemporal_load((const u32x4*)(PCUM + m * D + c0)), pc);
;             bf16_t* gp = P + m * DP + C_GR + c0; unpack8(*(const u32x4*)gp, gr);
; #pragma unroll
;             for (int e = 0; e < 8; ++e) { h[e] = hl[e] + pc[e] * carry[e]; o[e] = gelu_tanh(gr[e]) * h[e]; }
;             *(u32x4*)gp = pack8(o);
	v_fma_f32 v108, v108, v92, v92
	v_fma_f32 v109, v109, v93, v93
	v_fma_f32 v110, v110, v94, v94
	v_fma_f32 v111, v111, v95, v95
	v_mul_f32_e32 v104, 0x3fcc422a, v104
	v_mul_f32_e32 v105, 0x3fcc422a, v105
	v_mul_f32_e32 v106, 0x3fcc422a, v106
	v_mul_f32_e32 v107, 0x3fcc422a, v107
	v_mul_f32_e32 v108, 0x3fcc422a, v108
	v_mul_f32_e32 v109, 0x3fcc422a, v109
	v_mul_f32_e32 v110, 0x3fcc422a, v110
	v_mul_f32_e32 v111, 0x3fcc422a, v111
	v_mul_f32_e32 v104, 0xbfb8aa3b, v104
	v_mul_f32_e32 v105, 0xbfb8aa3b, v105
	v_mul_f32_e32 v106, 0xbfb8aa3b, v106
	v_mul_f32_e32 v107, 0xbfb8aa3b, v107
	v_mul_f32_e32 v108, 0xbfb8aa3b, v108
	v_mul_f32_e32 v109, 0xbfb8aa3b, v109
	v_mul_f32_e32 v110, 0xbfb8aa3b, v110
	v_mul_f32_e32 v111, 0xbfb8aa3b, v111
	v_exp_f32_e32 v104, v104
	v_exp_f32_e32 v105, v105
	v_exp_f32_e32 v106, v106
	v_exp_f32_e32 v107, v107
	v_exp_f32_e32 v108, v108
	v_exp_f32_e32 v109, v109
	v_exp_f32_e32 v110, v110
	v_exp_f32_e32 v111, v111
	v_add_f32_e32 v104, 1.0, v104
	v_add_f32_e32 v105, 1.0, v105
	v_add_f32_e32 v106, 1.0, v106
	v_add_f32_e32 v107, 1.0, v107
	v_add_f32_e32 v108, 1.0, v108
	v_add_f32_e32 v109, 1.0, v109
	v_add_f32_e32 v110, 1.0, v110
	v_add_f32_e32 v111, 1.0, v111
	v_rcp_f32_e32 v104, v104
	v_rcp_f32_e32 v105, v105
	v_rcp_f32_e32 v106, v106
	v_rcp_f32_e32 v107, v107
	v_rcp_f32_e32 v108, v108
	v_rcp_f32_e32 v109, v109
	v_rcp_f32_e32 v110, v110
	v_rcp_f32_e32 v111, v111
	v_mul_f32_e32 v104, v104, v88
	v_mul_f32_e32 v105, v105, v89
	v_mul_f32_e32 v106, v106, v90
	v_mul_f32_e32 v107, v107, v91
	v_mul_f32_e32 v108, v108, v92
	v_mul_f32_e32 v109, v109, v93
	v_mul_f32_e32 v110, v110, v94
	v_mul_f32_e32 v111, v111, v95
	v_mul_f32_e32 v104, v80, v104
	v_mul_f32_e32 v105, v81, v105
	v_mul_f32_e32 v106, v82, v106
	v_mul_f32_e32 v107, v83, v107
	v_mul_f32_e32 v108, v84, v108
	v_mul_f32_e32 v109, v85, v109
	v_mul_f32_e32 v110, v86, v110
	v_mul_f32_e32 v111, v87, v111
	v_cvt_pk_bf16_f32 v112, v104, v105
	v_cvt_pk_bf16_f32 v113, v106, v107
	v_cvt_pk_bf16_f32 v114, v108, v109
	v_cvt_pk_bf16_f32 v115, v110, v111
	global_store_dwordx4 v27, v[112:115], s[24:25]
	s_add_u32 s24, s24, 0x2800
	s_addc_u32 s25, s25, 0
	s_waitcnt vmcnt(6)
	v_lshlrev_b32_e32 v80, 16, v56
	v_and_b32_e32 v96, 0xffff0000, v56
	v_lshlrev_b32_e32 v81, 16, v57
	v_and_b32_e32 v97, 0xffff0000, v57
	v_lshlrev_b32_e32 v82, 16, v58
	v_and_b32_e32 v98, 0xffff0000, v58
	v_lshlrev_b32_e32 v83, 16, v59
	v_and_b32_e32 v99, 0xffff0000, v59
	v_lshlrev_b32_e32 v84, 16, v60
	v_and_b32_e32 v100, 0xffff0000, v60
	v_lshlrev_b32_e32 v85, 16, v61
	v_and_b32_e32 v101, 0xffff0000, v61
	v_lshlrev_b32_e32 v86, 16, v62
	v_and_b32_e32 v102, 0xffff0000, v62
	v_lshlrev_b32_e32 v87, 16, v63
	v_and_b32_e32 v103, 0xffff0000, v63
	v_lshlrev_b32_e32 v88, 16, v64
	v_and_b32_e32 v89, 0xffff0000, v64
	v_lshlrev_b32_e32 v90, 16, v65
	v_and_b32_e32 v91, 0xffff0000, v65
	v_lshlrev_b32_e32 v92, 16, v66
	v_and_b32_e32 v93, 0xffff0000, v66
	v_lshlrev_b32_e32 v94, 16, v67
	v_and_b32_e32 v95, 0xffff0000, v67
	v_fmac_f32_e32 v80, v96, v18
	v_fmac_f32_e32 v81, v97, v19
	v_fmac_f32_e32 v82, v98, v20
	v_fmac_f32_e32 v83, v99, v21
	v_fmac_f32_e32 v84, v100, v22
	v_fmac_f32_e32 v85, v101, v23
	v_fmac_f32_e32 v86, v102, v24
	v_fmac_f32_e32 v87, v103, v25
	v_mul_f32_e32 v104, 0x3d372713, v88
	v_mul_f32_e32 v105, 0x3d372713, v89
	v_mul_f32_e32 v106, 0x3d372713, v90
	v_mul_f32_e32 v107, 0x3d372713, v91
	v_mul_f32_e32 v108, 0x3d372713, v92
	v_mul_f32_e32 v109, 0x3d372713, v93
	v_mul_f32_e32 v110, 0x3d372713, v94
	v_mul_f32_e32 v111, 0x3d372713, v95
	v_mul_f32_e32 v104, v104, v88
	v_mul_f32_e32 v105, v105, v89
	v_mul_f32_e32 v106, v106, v90
	v_mul_f32_e32 v107, v107, v91
	v_mul_f32_e32 v108, v108, v92
	v_mul_f32_e32 v109, v109, v93
	v_mul_f32_e32 v110, v110, v94
	v_mul_f32_e32 v111, v111, v95
	v_fma_f32 v104, v104, v88, v88
	v_fma_f32 v105, v105, v89, v89
	v_fma_f32 v106, v106, v90, v90
	v_fma_f32 v107, v107, v91, v91
	v_fma_f32 v108, v108, v92, v92
	v_fma_f32 v109, v109, v93, v93
	v_fma_f32 v110, v110, v94, v94
	v_fma_f32 v111, v111, v95, v95
	v_mul_f32_e32 v104, 0x3fcc422a, v104
	v_mul_f32_e32 v105, 0x3fcc422a, v105
	v_mul_f32_e32 v106, 0x3fcc422a, v106
	v_mul_f32_e32 v107, 0x3fcc422a, v107
	v_mul_f32_e32 v108, 0x3fcc422a, v108
	v_mul_f32_e32 v109, 0x3fcc422a, v109
	v_mul_f32_e32 v110, 0x3fcc422a, v110
	v_mul_f32_e32 v111, 0x3fcc422a, v111
	v_mul_f32_e32 v104, 0xbfb8aa3b, v104
	v_mul_f32_e32 v105, 0xbfb8aa3b, v105
	v_mul_f32_e32 v106, 0xbfb8aa3b, v106
	v_mul_f32_e32 v107, 0xbfb8aa3b, v107
	v_mul_f32_e32 v108, 0xbfb8aa3b, v108
	v_mul_f32_e32 v109, 0xbfb8aa3b, v109
	v_mul_f32_e32 v110, 0xbfb8aa3b, v110
	v_mul_f32_e32 v111, 0xbfb8aa3b, v111
	v_exp_f32_e32 v104, v104
	v_exp_f32_e32 v105, v105
	v_exp_f32_e32 v106, v106
	v_exp_f32_e32 v107, v107
	v_exp_f32_e32 v108, v108
	v_exp_f32_e32 v109, v109
	v_exp_f32_e32 v110, v110
	v_exp_f32_e32 v111, v111
	v_add_f32_e32 v104, 1.0, v104
	v_add_f32_e32 v105, 1.0, v105
	v_add_f32_e32 v106, 1.0, v106
	v_add_f32_e32 v107, 1.0, v107
	v_add_f32_e32 v108, 1.0, v108
	v_add_f32_e32 v109, 1.0, v109
	v_add_f32_e32 v110, 1.0, v110
	v_add_f32_e32 v111, 1.0, v111
	v_rcp_f32_e32 v104, v104
	v_rcp_f32_e32 v105, v105
	v_rcp_f32_e32 v106, v106
	v_rcp_f32_e32 v107, v107
	v_rcp_f32_e32 v108, v108
	v_rcp_f32_e32 v109, v109
	v_rcp_f32_e32 v110, v110
	v_rcp_f32_e32 v111, v111
	v_mul_f32_e32 v104, v104, v88
	v_mul_f32_e32 v105, v105, v89
	v_mul_f32_e32 v106, v106, v90
	v_mul_f32_e32 v107, v107, v91
	v_mul_f32_e32 v108, v108, v92
	v_mul_f32_e32 v109, v109, v93
	v_mul_f32_e32 v110, v110, v94
	v_mul_f32_e32 v111, v111, v95
	v_mul_f32_e32 v104, v80, v104
	v_mul_f32_e32 v105, v81, v105
	v_mul_f32_e32 v106, v82, v106
	v_mul_f32_e32 v107, v83, v107
	v_mul_f32_e32 v108, v84, v108
	v_mul_f32_e32 v109, v85, v109
	v_mul_f32_e32 v110, v86, v110
	v_mul_f32_e32 v111, v87, v111
	v_cvt_pk_bf16_f32 v112, v104, v105
	v_cvt_pk_bf16_f32 v113, v106, v107
	v_cvt_pk_bf16_f32 v114, v108, v109
	v_cvt_pk_bf16_f32 v115, v110, v111
	global_store_dwordx4 v27, v[112:115], s[24:25]
	s_add_u32 s24, s24, 0x2800
	s_addc_u32 s25, s25, 0
	s_waitcnt vmcnt(3)
; __device__ __forceinline__ u32x4 pack8(const float (&f)[8]) { u32x4 o; o.x = cvt_pk_bf16(f[0], f[1]); o.y = cvt_pk_bf16(f[2], f[3]); o.z = cvt_pk_bf16(f[4], f[5]); o.w = cvt_pk_bf16(f[6], f[7]); return o; }
; __device__ __forceinline__ float gelu_tanh(float x) { return x * sigmoidf_(1.5957691216057308f * (x + 0.044715f * x * x * x)); }
; __device__ __forceinline__ void fixup_phase(KP p, int l) {
;     ...
;     for (int it = gt; it < (M / 16) * 128; it += NT) {
;         const int tile = it >> 7, c0 = (it & 127) * 8, m0 = tile * 16;
;     ...
;         for (int i = 0; i < 16; ++i) {
;             const size_t m = (size_t)(m0 + i);
;             float hl[8], pc[8], gr[8], o[8], h[8];
;             unpack8(__builtin_nontemporal_load((const u32x4*)(HLOC + m * D + c0)), hl); unpack8(__builtin_nontemporal_load((const u32x4*)(PCUM + m * D + c0)), pc);
;             bf16_t* gp = P + m * DP + C_GR + c0; unpack8(*(const u32x4*)gp, gr);
; #pragma unroll
;             for (int e = 0; e < 8; ++e) { h[e] = hl[e] + pc[e] * carry[e]; o[e] = gelu_tanh(gr[e]) * h[e]; }
;             *(u32x4*)gp = pack8(o);
;             if (tile < 1032 && t0 + i == TP - 1) store8f(p->out + O_PRG + (size_t)(l * NB + b) * D + c0, h);
;         }
	v_lshlrev_b32_e32 v80, 16, v68
	v_and_b32_e32 v96, 0xffff0000, v68
	v_lshlrev_b32_e32 v81, 16, v69
	v_and_b32_e32 v97, 0xffff0000, v69
	v_lshlrev_b32_e32 v82, 16, v70
	v_and_b32_e32 v98, 0xffff0000, v70
	v_lshlrev_b32_e32 v83, 16, v71
	v_and_b32_e32 v99, 0xffff0000, v71
	v_lshlrev_b32_e32 v84, 16, v72
	v_and_b32_e32 v100, 0xffff0000, v72
	v_lshlrev_b32_e32 v85, 16, v73
	v_and_b32_e32 v101, 0xffff0000, v73
	v_lshlrev_b32_e32 v86, 16, v74
	v_and_b32_e32 v102, 0xffff0000, v74
	v_lshlrev_b32_e32 v87, 16, v75
	v_and_b32_e32 v103, 0xffff0000, v75
	v_lshlrev_b32_e32 v88, 16, v76
	v_and_b32_e32 v89, 0xffff0000, v76
	v_lshlrev_b32_e32 v90, 16, v77
	v_and_b32_e32 v91, 0xffff0000, v77
	v_lshlrev_b32_e32 v92, 16, v78
	v_and_b32_e32 v93, 0xffff0000, v78
	v_lshlrev_b32_e32 v94, 16, v79
	v_and_b32_e32 v95, 0xffff0000, v79
	v_fmac_f32_e32 v80, v96, v18
	v_fmac_f32_e32 v81, v97, v19
	v_fmac_f32_e32 v82, v98, v20
	v_fmac_f32_e32 v83, v99, v21
	v_fmac_f32_e32 v84, v100, v22
	v_fmac_f32_e32 v85, v101, v23
	v_fmac_f32_e32 v86, v102, v24
	v_fmac_f32_e32 v87, v103, v25
	v_mul_f32_e32 v104, 0x3d372713, v88
	v_mul_f32_e32 v105, 0x3d372713, v89
	v_mul_f32_e32 v106, 0x3d372713, v90
	v_mul_f32_e32 v107, 0x3d372713, v91
	v_mul_f32_e32 v108, 0x3d372713, v92
	v_mul_f32_e32 v109, 0x3d372713, v93
	v_mul_f32_e32 v110, 0x3d372713, v94
	v_mul_f32_e32 v111, 0x3d372713, v95
	v_mul_f32_e32 v104, v104, v88
	v_mul_f32_e32 v105, v105, v89
	v_mul_f32_e32 v106, v106, v90
	v_mul_f32_e32 v107, v107, v91
	v_mul_f32_e32 v108, v108, v92
	v_mul_f32_e32 v109, v109, v93
	v_mul_f32_e32 v110, v110, v94
	v_mul_f32_e32 v111, v111, v95
	v_fma_f32 v104, v104, v88, v88
	v_fma_f32 v105, v105, v89, v89
	v_fma_f32 v106, v106, v90, v90
	v_fma_f32 v107, v107, v91, v91
	v_fma_f32 v108, v108, v92, v92
	v_fma_f32 v109, v109, v93, v93
	v_fma_f32 v110, v110, v94, v94
	v_fma_f32 v111, v111, v95, v95
	v_mul_f32_e32 v104, 0x3fcc422a, v104
	v_mul_f32_e32 v105, 0x3fcc422a, v105
	v_mul_f32_e32 v106, 0x3fcc422a, v106
	v_mul_f32_e32 v107, 0x3fcc422a, v107
	v_mul_f32_e32 v108, 0x3fcc422a, v108
	v_mul_f32_e32 v109, 0x3fcc422a, v109
	v_mul_f32_e32 v110, 0x3fcc422a, v110
	v_mul_f32_e32 v111, 0x3fcc422a, v111
	v_mul_f32_e32 v104, 0xbfb8aa3b, v104
	v_mul_f32_e32 v105, 0xbfb8aa3b, v105
	v_mul_f32_e32 v106, 0xbfb8aa3b, v106
	v_mul_f32_e32 v107, 0xbfb8aa3b, v107
	v_mul_f32_e32 v108, 0xbfb8aa3b, v108
	v_mul_f32_e32 v109, 0xbfb8aa3b, v109
	v_mul_f32_e32 v110, 0xbfb8aa3b, v110
	v_mul_f32_e32 v111, 0xbfb8aa3b, v111
	v_exp_f32_e32 v104, v104
	v_exp_f32_e32 v105, v105
	v_exp_f32_e32 v106, v106
	v_exp_f32_e32 v107, v107
	v_exp_f32_e32 v108, v108
	v_exp_f32_e32 v109, v109
	v_exp_f32_e32 v110, v110
	v_exp_f32_e32 v111, v111
	v_add_f32_e32 v104, 1.0, v104
	v_add_f32_e32 v105, 1.0, v105
	v_add_f32_e32 v106, 1.0, v106
	v_add_f32_e32 v107, 1.0, v107
	v_add_f32_e32 v108, 1.0, v108
	v_add_f32_e32 v109, 1.0, v109
	v_add_f32_e32 v110, 1.0, v110
	v_add_f32_e32 v111, 1.0, v111
	v_rcp_f32_e32 v104, v104
	v_rcp_f32_e32 v105, v105
	v_rcp_f32_e32 v106, v106
	v_rcp_f32_e32 v107, v107
	v_rcp_f32_e32 v108, v108
	v_rcp_f32_e32 v109, v109
	v_rcp_f32_e32 v110, v110
	v_rcp_f32_e32 v111, v111
	v_mul_f32_e32 v104, v104, v88
	v_mul_f32_e32 v105, v105, v89
	v_mul_f32_e32 v106, v106, v90
	v_mul_f32_e32 v107, v107, v91
	v_mul_f32_e32 v108, v108, v92
	v_mul_f32_e32 v109, v109, v93
	v_mul_f32_e32 v110, v110, v94
	v_mul_f32_e32 v111, v111, v95
	v_mul_f32_e32 v104, v80, v104
	v_mul_f32_e32 v105, v81, v105
	v_mul_f32_e32 v106, v82, v106
	v_mul_f32_e32 v107, v83, v107
	v_mul_f32_e32 v108, v84, v108
	v_mul_f32_e32 v109, v85, v109
	v_mul_f32_e32 v110, v86, v110
	v_mul_f32_e32 v111, v87, v111
	v_cvt_pk_bf16_f32 v112, v104, v105
	v_cvt_pk_bf16_f32 v113, v106, v107
	v_cvt_pk_bf16_f32 v114, v108, v109
	v_cvt_pk_bf16_f32 v115, v110, v111
	global_store_dwordx4 v27, v[112:115], s[24:25]
	s_cmp_eq_u32 s43, 0
	s_cbranch_scc1 .Lfx_noprg
	s_lshl_b32 s44, s18, 12
	s_lshl_b32 s23, s10, 12
	s_add_i32 s44, s44, s23
	s_add_u32 s98, s72, 0x4120000
	s_addc_u32 s99, s73, 0
	s_add_u32 s98, s98, s44
	s_addc_u32 s99, s99, 0
	global_store_dwordx4 v31, v[80:83], s[98:99]
	global_store_dwordx4 v31, v[84:87], s[98:99] offset:16
.Lfx_noprg:
	s_add_u32 s24, s24, 0x2800
	s_addc_u32 s25, s25, 0
	s_cmp_lt_u32 s4, 32
	s_cbranch_scc0 .Lfx_done
	s_mov_b32 s87, 1
	s_lshr_b32 s57, s4, 1
	s_add_i32 s57, s57, 0x400
	s_lshl_b32 s57, s57, 7
	s_and_b32 s23, s4, 1
	s_lshl_b32 s23, s23, 6
	s_add_i32 s57, s57, s23
	s_branch .Lfx_loop
